# GEMM K-loops: the SP1 load segment issues its two LDS-DMA pieces first (right after the barrier), before the 16 ds_read_b128
# baseline (speedup 1.0000x reference)
.LBB0_226:
	s_add_i32 vcc_lo, s82, 2
	s_add_u32 s20, s66, 0xffff0080
	s_addc_u32 s21, s67, -1
	s_add_i32 s52, 0, 0x10000
	s_cmp_eq_u32 s60, s82
	s_cselect_b32 s87, s39, s21
	s_cselect_b32 s86, s41, s20
	s_cselect_b32 s83, s88, s95
	s_cselect_b32 s82, s89, s94
	s_add_i32 s53, 0, 0x14000
	v_lshl_add_u64 v[244:245], s[66:67], 0, v[134:135]
	s_add_i32 m0, s13, 0xc000
	s_nop 0
	global_load_lds_dwordx4 v[244:245], off
	v_lshl_add_u64 v[246:247], s[66:67], 0, v[136:137]
	s_add_i32 m0, s13, 0xe000
	s_nop 0
	global_load_lds_dwordx4 v[246:247], off
	v_add_u32_e32 v154, s52, v140
	v_add_u32_e32 v170, s53, v140
	ds_read_b128 v[142:145], v154
	ds_read_b128 v[146:149], v154 offset:1024
	ds_read_b128 v[150:153], v154 offset:2048
	ds_read_b128 v[154:157], v154 offset:3072
	ds_read_b128 v[158:161], v170
	ds_read_b128 v[162:165], v170 offset:1024
	ds_read_b128 v[166:169], v170 offset:2048
	ds_read_b128 v[170:173], v170 offset:3072
	ds_read_b128 v[174:177], v141
	ds_read_b128 v[178:181], v141 offset:1024
	ds_read_b128 v[182:185], v141 offset:2048
	ds_read_b128 v[202:205], v141 offset:3072
	ds_read_b128 v[216:219], v141 offset:4096
	ds_read_b128 v[220:223], v141 offset:5120
	ds_read_b128 v[224:227], v141 offset:6144
	ds_read_b128 v[228:231], v141 offset:7168
	s_waitcnt vmcnt(8)
	s_waitcnt lgkmcnt(0)


	s_barrier
	s_setprio 1
	s_waitcnt lgkmcnt(0)
	v_mfma_f32_16x16x32_bf16 v[120:123], v[142:145], v[174:177], v[120:123]
	v_mfma_f32_16x16x32_bf16 v[124:127], v[150:153], v[174:177], v[124:127]
	v_mfma_f32_16x16x32_bf16 v[108:111], v[142:145], v[182:185], v[108:111]
	v_mfma_f32_16x16x32_bf16 v[104:107], v[150:153], v[182:185], v[104:107]
	v_mfma_f32_16x16x32_bf16 v[92:95], v[142:145], v[216:219], v[92:95]
	v_mfma_f32_16x16x32_bf16 v[88:91], v[150:153], v[216:219], v[88:91]
	v_mfma_f32_16x16x32_bf16 v[76:79], v[142:145], v[224:227], v[76:79]
	v_mfma_f32_16x16x32_bf16 v[72:75], v[150:153], v[224:227], v[72:75]
	v_mfma_f32_16x16x32_bf16 v[120:123], v[146:149], v[178:181], v[120:123]
	v_mfma_f32_16x16x32_bf16 v[124:127], v[154:157], v[178:181], v[124:127]
	v_mfma_f32_16x16x32_bf16 v[108:111], v[146:149], v[202:205], v[108:111]
	v_mfma_f32_16x16x32_bf16 v[104:107], v[154:157], v[202:205], v[104:107]
	v_mfma_f32_16x16x32_bf16 v[92:95], v[146:149], v[220:223], v[92:95]
	v_mfma_f32_16x16x32_bf16 v[88:91], v[154:157], v[220:223], v[88:91]
	v_mfma_f32_16x16x32_bf16 v[76:79], v[146:149], v[228:231], v[76:79]
	v_mfma_f32_16x16x32_bf16 v[72:75], v[154:157], v[228:231], v[72:75]
	s_setprio 0
	s_setprio 1
	v_mfma_f32_16x16x32_bf16 v[116:119], v[158:161], v[174:177], v[116:119]
	v_mfma_f32_16x16x32_bf16 v[112:115], v[166:169], v[174:177], v[112:115]
	v_mfma_f32_16x16x32_bf16 v[100:103], v[158:161], v[182:185], v[100:103]
	v_mfma_f32_16x16x32_bf16 v[96:99], v[166:169], v[182:185], v[96:99]
	v_mfma_f32_16x16x32_bf16 v[84:87], v[158:161], v[216:219], v[84:87]
	v_mfma_f32_16x16x32_bf16 v[80:83], v[166:169], v[216:219], v[80:83]
	v_mfma_f32_16x16x32_bf16 v[68:71], v[158:161], v[224:227], v[68:71]
	v_mfma_f32_16x16x32_bf16 v[64:67], v[166:169], v[224:227], v[64:67]
	v_mfma_f32_16x16x32_bf16 v[116:119], v[162:165], v[178:181], v[116:119]
	v_mfma_f32_16x16x32_bf16 v[112:115], v[170:173], v[178:181], v[112:115]
	v_mfma_f32_16x16x32_bf16 v[100:103], v[162:165], v[202:205], v[100:103]
	v_mfma_f32_16x16x32_bf16 v[96:99], v[170:173], v[202:205], v[96:99]
	v_mfma_f32_16x16x32_bf16 v[84:87], v[162:165], v[220:223], v[84:87]
	v_mfma_f32_16x16x32_bf16 v[80:83], v[170:173], v[220:223], v[80:83]
	v_mfma_f32_16x16x32_bf16 v[68:71], v[162:165], v[228:231], v[68:71]
	v_mfma_f32_16x16x32_bf16 v[64:67], v[170:173], v[228:231], v[64:67]
	s_setprio 0
	s_barrier
	s_add_i32 s20, s52, s12
	v_lshl_add_u64 v[186:187], s[82:83], 0, v[188:189]
	s_mov_b32 m0, s20
	ds_read_b128 v[174:177], v141 offset:16384
	ds_read_b128 v[178:181], v141 offset:17408
	ds_read_b128 v[182:185], v141 offset:18432
	ds_read_b128 v[202:205], v141 offset:19456
	ds_read_b128 v[216:219], v141 offset:20480
	ds_read_b128 v[220:223], v141 offset:21504
	ds_read_b128 v[224:227], v141 offset:22528
	ds_read_b128 v[228:231], v141 offset:23552
	global_load_lds_dwordx4 v[186:187], off
	s_add_i32 m0, s20, 0x2000
	s_add_u32 s20, s82, 0x10000
	v_lshl_add_u64 v[194:195], s[82:83], 0, v[128:129]
	s_addc_u32 s21, s83, 0
	s_add_i32 s52, s53, s12
	global_load_lds_dwordx4 v[194:195], off
	v_lshl_add_u64 v[196:197], s[20:21], 0, v[188:189]
	s_mov_b32 m0, s52
	v_lshl_add_u64 v[232:233], s[86:87], 0, v[130:131]
	global_load_lds_dwordx4 v[196:197], off
	v_lshl_add_u64 v[196:197], s[20:21], 0, v[128:129]
	s_add_i32 m0, s52, 0x2000
	s_nop 0
	global_load_lds_dwordx4 v[196:197], off
	v_lshl_add_u64 v[196:197], s[86:87], 0, v[132:133]
	s_mov_b32 m0, s13
	s_nop 0
	global_load_lds_dwordx4 v[196:197], off
	s_mov_b32 m0, s28
	s_nop 0
	global_load_lds_dwordx4 v[232:233], off
	s_waitcnt vmcnt(8)
	s_waitcnt lgkmcnt(0)
	s_barrier
	s_setprio 1
	s_waitcnt lgkmcnt(0)
	v_mfma_f32_16x16x32_bf16 v[60:63], v[142:145], v[174:177], v[60:63]
	v_mfma_f32_16x16x32_bf16 v[56:59], v[150:153], v[174:177], v[56:59]
	v_mfma_f32_16x16x32_bf16 v[44:47], v[142:145], v[182:185], v[44:47]
	v_mfma_f32_16x16x32_bf16 v[40:43], v[150:153], v[182:185], v[40:43]
	v_mfma_f32_16x16x32_bf16 v[28:31], v[142:145], v[216:219], v[28:31]
	v_mfma_f32_16x16x32_bf16 v[24:27], v[150:153], v[216:219], v[24:27]
	v_mfma_f32_16x16x32_bf16 v[12:15], v[142:145], v[224:227], v[12:15]
	v_mfma_f32_16x16x32_bf16 v[8:11], v[150:153], v[224:227], v[8:11]
	v_mfma_f32_16x16x32_bf16 v[60:63], v[146:149], v[178:181], v[60:63]
	v_mfma_f32_16x16x32_bf16 v[56:59], v[154:157], v[178:181], v[56:59]
	v_mfma_f32_16x16x32_bf16 v[44:47], v[146:149], v[202:205], v[44:47]
	v_mfma_f32_16x16x32_bf16 v[40:43], v[154:157], v[202:205], v[40:43]
	v_mfma_f32_16x16x32_bf16 v[28:31], v[146:149], v[220:223], v[28:31]
	v_mfma_f32_16x16x32_bf16 v[24:27], v[154:157], v[220:223], v[24:27]
	v_mfma_f32_16x16x32_bf16 v[12:15], v[146:149], v[228:231], v[12:15]
	v_mfma_f32_16x16x32_bf16 v[8:11], v[154:157], v[228:231], v[8:11]
	s_setprio 0
	s_setprio 1
	v_mfma_f32_16x16x32_bf16 v[52:55], v[158:161], v[174:177], v[52:55]
	v_mfma_f32_16x16x32_bf16 v[48:51], v[166:169], v[174:177], v[48:51]
	v_mfma_f32_16x16x32_bf16 v[36:39], v[158:161], v[182:185], v[36:39]
	v_mfma_f32_16x16x32_bf16 v[32:35], v[166:169], v[182:185], v[32:35]
	v_mfma_f32_16x16x32_bf16 v[20:23], v[158:161], v[216:219], v[20:23]
	v_mfma_f32_16x16x32_bf16 v[16:19], v[166:169], v[216:219], v[16:19]
	v_mfma_f32_16x16x32_bf16 v[4:7], v[158:161], v[224:227], v[4:7]
	v_mfma_f32_16x16x32_bf16 v[0:3], v[166:169], v[224:227], v[0:3]
	v_mfma_f32_16x16x32_bf16 v[52:55], v[162:165], v[178:181], v[52:55]
	v_mfma_f32_16x16x32_bf16 v[48:51], v[170:173], v[178:181], v[48:51]
	v_mfma_f32_16x16x32_bf16 v[36:39], v[162:165], v[202:205], v[36:39]
	v_mfma_f32_16x16x32_bf16 v[32:35], v[170:173], v[202:205], v[32:35]
	v_mfma_f32_16x16x32_bf16 v[20:23], v[162:165], v[220:223], v[20:23]
	v_mfma_f32_16x16x32_bf16 v[16:19], v[170:173], v[220:223], v[16:19]
	v_mfma_f32_16x16x32_bf16 v[4:7], v[162:165], v[228:231], v[4:7]
	v_mfma_f32_16x16x32_bf16 v[0:3], v[170:173], v[228:231], v[0:3]
	s_setprio 0
	s_barrier
	s_add_i32 s52, 0, 0x18000
	s_add_i32 s53, 0, 0x1c000
	s_add_u32 s20, s86, 0x10000
	s_addc_u32 s21, s87, 0
	s_mov_b32 m0, s46
	v_lshl_add_u64 v[244:245], s[20:21], 0, v[132:133]
	global_load_lds_dwordx4 v[244:245], off
	v_lshl_add_u64 v[246:247], s[20:21], 0, v[130:131]
	s_mov_b32 m0, s47
	s_nop 0
	global_load_lds_dwordx4 v[246:247], off
	v_add_u32_e32 v154, s52, v140
	v_add_u32_e32 v170, s53, v140
	ds_read_b128 v[142:145], v154
	ds_read_b128 v[146:149], v154 offset:1024
	ds_read_b128 v[150:153], v154 offset:2048
	ds_read_b128 v[154:157], v154 offset:3072
	ds_read_b128 v[158:161], v170
	ds_read_b128 v[162:165], v170 offset:1024
	ds_read_b128 v[166:169], v170 offset:2048
	ds_read_b128 v[170:173], v170 offset:3072
	ds_read_b128 v[174:177], v141 offset:32768
	ds_read_b128 v[178:181], v141 offset:33792
	ds_read_b128 v[182:185], v141 offset:34816
	ds_read_b128 v[202:205], v141 offset:35840
	ds_read_b128 v[216:219], v141 offset:36864
	ds_read_b128 v[220:223], v141 offset:37888
	ds_read_b128 v[224:227], v141 offset:38912
	ds_read_b128 v[228:231], v141 offset:39936
	s_waitcnt vmcnt(8)
	s_waitcnt lgkmcnt(0)


	s_barrier
	s_setprio 1
	s_waitcnt lgkmcnt(0)
	v_mfma_f32_16x16x32_bf16 v[120:123], v[142:145], v[174:177], v[120:123]
	v_mfma_f32_16x16x32_bf16 v[124:127], v[150:153], v[174:177], v[124:127]
	v_mfma_f32_16x16x32_bf16 v[108:111], v[142:145], v[182:185], v[108:111]
	v_mfma_f32_16x16x32_bf16 v[104:107], v[150:153], v[182:185], v[104:107]
	v_mfma_f32_16x16x32_bf16 v[92:95], v[142:145], v[216:219], v[92:95]
	v_mfma_f32_16x16x32_bf16 v[88:91], v[150:153], v[216:219], v[88:91]
	v_mfma_f32_16x16x32_bf16 v[76:79], v[142:145], v[224:227], v[76:79]
	v_mfma_f32_16x16x32_bf16 v[72:75], v[150:153], v[224:227], v[72:75]
	v_mfma_f32_16x16x32_bf16 v[120:123], v[146:149], v[178:181], v[120:123]
	v_mfma_f32_16x16x32_bf16 v[124:127], v[154:157], v[178:181], v[124:127]
	v_mfma_f32_16x16x32_bf16 v[108:111], v[146:149], v[202:205], v[108:111]
	v_mfma_f32_16x16x32_bf16 v[104:107], v[154:157], v[202:205], v[104:107]
	v_mfma_f32_16x16x32_bf16 v[92:95], v[146:149], v[220:223], v[92:95]
	v_mfma_f32_16x16x32_bf16 v[88:91], v[154:157], v[220:223], v[88:91]
	v_mfma_f32_16x16x32_bf16 v[76:79], v[146:149], v[228:231], v[76:79]
	v_mfma_f32_16x16x32_bf16 v[72:75], v[154:157], v[228:231], v[72:75]
	s_setprio 0
	s_setprio 1
	v_mfma_f32_16x16x32_bf16 v[116:119], v[158:161], v[174:177], v[116:119]
	v_mfma_f32_16x16x32_bf16 v[112:115], v[166:169], v[174:177], v[112:115]
	v_mfma_f32_16x16x32_bf16 v[100:103], v[158:161], v[182:185], v[100:103]
	v_mfma_f32_16x16x32_bf16 v[96:99], v[166:169], v[182:185], v[96:99]
	v_mfma_f32_16x16x32_bf16 v[84:87], v[158:161], v[216:219], v[84:87]
	v_mfma_f32_16x16x32_bf16 v[80:83], v[166:169], v[216:219], v[80:83]
	v_mfma_f32_16x16x32_bf16 v[68:71], v[158:161], v[224:227], v[68:71]
	v_mfma_f32_16x16x32_bf16 v[64:67], v[166:169], v[224:227], v[64:67]
	v_mfma_f32_16x16x32_bf16 v[116:119], v[162:165], v[178:181], v[116:119]
	v_mfma_f32_16x16x32_bf16 v[112:115], v[170:173], v[178:181], v[112:115]
	v_mfma_f32_16x16x32_bf16 v[100:103], v[162:165], v[202:205], v[100:103]
	v_mfma_f32_16x16x32_bf16 v[96:99], v[170:173], v[202:205], v[96:99]
	v_mfma_f32_16x16x32_bf16 v[84:87], v[162:165], v[220:223], v[84:87]
	v_mfma_f32_16x16x32_bf16 v[80:83], v[170:173], v[220:223], v[80:83]
	v_mfma_f32_16x16x32_bf16 v[68:71], v[162:165], v[228:231], v[68:71]
	v_mfma_f32_16x16x32_bf16 v[64:67], v[170:173], v[228:231], v[64:67]
	s_setprio 0
	s_barrier
	s_add_i32 s20, s52, s12
	v_lshl_add_u64 v[186:187], v[186:187], 0, s[62:63]
	s_mov_b32 m0, s20
	ds_read_b128 v[174:177], v141 offset:49152
	ds_read_b128 v[178:181], v141 offset:50176
	ds_read_b128 v[182:185], v141 offset:51200
	ds_read_b128 v[202:205], v141 offset:52224
	ds_read_b128 v[216:219], v141 offset:53248
	ds_read_b128 v[220:223], v141 offset:54272
	ds_read_b128 v[224:227], v141 offset:55296
	ds_read_b128 v[228:231], v141 offset:56320
	global_load_lds_dwordx4 v[186:187], off
	s_add_i32 m0, s20, 0x2000
	s_add_u32 s20, s82, 0x10080
	v_lshl_add_u64 v[186:187], v[194:195], 0, s[62:63]
	s_addc_u32 s21, s83, 0
	s_add_i32 s52, s53, s12
	global_load_lds_dwordx4 v[186:187], off
	v_lshl_add_u64 v[186:187], s[20:21], 0, v[188:189]
	s_mov_b32 m0, s52
	s_nop 0
	global_load_lds_dwordx4 v[186:187], off
	v_lshl_add_u64 v[186:187], s[20:21], 0, v[128:129]
	s_add_i32 m0, s52, 0x2000
	s_nop 0
	global_load_lds_dwordx4 v[186:187], off
	v_lshl_add_u64 v[186:187], v[196:197], 0, s[62:63]
	s_mov_b32 m0, s56
	s_nop 0
	global_load_lds_dwordx4 v[186:187], off
	v_lshl_add_u64 v[186:187], v[232:233], 0, s[62:63]
	s_mov_b32 m0, s57
	s_nop 0
	global_load_lds_dwordx4 v[186:187], off
	s_waitcnt vmcnt(8)
	s_waitcnt lgkmcnt(0)
	s_barrier
	s_setprio 1
	s_waitcnt lgkmcnt(0)
	v_mfma_f32_16x16x32_bf16 v[60:63], v[142:145], v[174:177], v[60:63]
	v_mfma_f32_16x16x32_bf16 v[56:59], v[150:153], v[174:177], v[56:59]
	v_mfma_f32_16x16x32_bf16 v[44:47], v[142:145], v[182:185], v[44:47]
	v_mfma_f32_16x16x32_bf16 v[40:43], v[150:153], v[182:185], v[40:43]
	v_mfma_f32_16x16x32_bf16 v[28:31], v[142:145], v[216:219], v[28:31]
	v_mfma_f32_16x16x32_bf16 v[24:27], v[150:153], v[216:219], v[24:27]
	v_mfma_f32_16x16x32_bf16 v[12:15], v[142:145], v[224:227], v[12:15]
	v_mfma_f32_16x16x32_bf16 v[8:11], v[150:153], v[224:227], v[8:11]
	v_mfma_f32_16x16x32_bf16 v[60:63], v[146:149], v[178:181], v[60:63]
	v_mfma_f32_16x16x32_bf16 v[56:59], v[154:157], v[178:181], v[56:59]
	v_mfma_f32_16x16x32_bf16 v[44:47], v[146:149], v[202:205], v[44:47]
	v_mfma_f32_16x16x32_bf16 v[40:43], v[154:157], v[202:205], v[40:43]
	v_mfma_f32_16x16x32_bf16 v[28:31], v[146:149], v[220:223], v[28:31]
	v_mfma_f32_16x16x32_bf16 v[24:27], v[154:157], v[220:223], v[24:27]
	v_mfma_f32_16x16x32_bf16 v[12:15], v[146:149], v[228:231], v[12:15]
	v_mfma_f32_16x16x32_bf16 v[8:11], v[154:157], v[228:231], v[8:11]
	s_setprio 0
	s_setprio 1
	v_mfma_f32_16x16x32_bf16 v[52:55], v[158:161], v[174:177], v[52:55]
	v_mfma_f32_16x16x32_bf16 v[48:51], v[166:169], v[174:177], v[48:51]
	v_mfma_f32_16x16x32_bf16 v[36:39], v[158:161], v[182:185], v[36:39]
	v_mfma_f32_16x16x32_bf16 v[32:35], v[166:169], v[182:185], v[32:35]
	v_mfma_f32_16x16x32_bf16 v[20:23], v[158:161], v[216:219], v[20:23]
	v_mfma_f32_16x16x32_bf16 v[16:19], v[166:169], v[216:219], v[16:19]
	v_mfma_f32_16x16x32_bf16 v[4:7], v[158:161], v[224:227], v[4:7]
	v_mfma_f32_16x16x32_bf16 v[0:3], v[166:169], v[224:227], v[0:3]
	v_mfma_f32_16x16x32_bf16 v[52:55], v[162:165], v[178:181], v[52:55]
	v_mfma_f32_16x16x32_bf16 v[48:51], v[170:173], v[178:181], v[48:51]
	v_mfma_f32_16x16x32_bf16 v[36:39], v[162:165], v[202:205], v[36:39]
	v_mfma_f32_16x16x32_bf16 v[32:35], v[170:173], v[202:205], v[32:35]
	v_mfma_f32_16x16x32_bf16 v[20:23], v[162:165], v[220:223], v[20:23]
	v_mfma_f32_16x16x32_bf16 v[16:19], v[170:173], v[220:223], v[16:19]
	v_mfma_f32_16x16x32_bf16 v[4:7], v[162:165], v[228:231], v[4:7]
	v_mfma_f32_16x16x32_bf16 v[0:3], v[170:173], v[228:231], v[0:3]
	s_setprio 0
	s_barrier
	s_add_u32 s66, s66, 0x100
	s_addc_u32 s67, s67, 0
	s_add_u32 s94, s94, 0x100
	s_addc_u32 s95, s95, 0
	s_cmp_ge_i32 vcc_lo, s48
	s_mov_b32 s82, vcc_lo
	s_cbranch_scc0 .LBB0_226
	s_mov_b64 s[88:89], 0x8000

.LBB0_247:
	s_add_i32 s61, s40, 2
	s_add_u32 s20, s38, 0xfffc0080
	s_addc_u32 s21, s39, -1
	s_add_i32 s52, 0, 0x10000
	s_cmp_eq_u32 s49, s40
	s_cselect_b32 s59, s35, s21
	s_cselect_b32 s58, s67, s20
	s_cselect_b32 s41, vcc_lo, s83
	s_cselect_b32 s40, vcc_hi, s82
	s_add_i32 s53, 0, 0x14000
	v_lshl_add_u64 v[244:245], s[38:39], 0, v[136:137]
	s_add_i32 m0, s46, 0xc000
	s_nop 0
	global_load_lds_dwordx4 v[244:245], off
	v_lshl_add_u64 v[246:247], s[38:39], 0, v[138:139]
	s_add_i32 m0, s46, 0xe000
	s_nop 0
	global_load_lds_dwordx4 v[246:247], off
	v_add_u32_e32 v148, s52, v168
	v_add_u32_e32 v164, s53, v168
	ds_read_b128 v[128:131], v148
	ds_read_b128 v[140:143], v148 offset:1024
	ds_read_b128 v[144:147], v148 offset:2048
	ds_read_b128 v[148:151], v148 offset:3072
	ds_read_b128 v[152:155], v164
	ds_read_b128 v[156:159], v164 offset:1024
	ds_read_b128 v[160:163], v164 offset:2048
	ds_read_b128 v[170:173], v164 offset:3072
	ds_read_b128 v[174:177], v169
	ds_read_b128 v[178:181], v169 offset:1024
	ds_read_b128 v[182:185], v169 offset:2048
	ds_read_b128 v[202:205], v169 offset:3072
	ds_read_b128 v[216:219], v169 offset:4096
	ds_read_b128 v[220:223], v169 offset:5120
	ds_read_b128 v[224:227], v169 offset:6144
	ds_read_b128 v[228:231], v169 offset:7168
	s_waitcnt vmcnt(8)
	s_waitcnt lgkmcnt(0)


	s_barrier
	s_setprio 1
	s_waitcnt lgkmcnt(0)
	v_mfma_f32_16x16x32_bf16 v[120:123], v[128:131], v[174:177], v[120:123]
	v_mfma_f32_16x16x32_bf16 v[124:127], v[144:147], v[174:177], v[124:127]
	v_mfma_f32_16x16x32_bf16 v[108:111], v[128:131], v[182:185], v[108:111]
	v_mfma_f32_16x16x32_bf16 v[104:107], v[144:147], v[182:185], v[104:107]
	v_mfma_f32_16x16x32_bf16 v[92:95], v[128:131], v[216:219], v[92:95]
	v_mfma_f32_16x16x32_bf16 v[88:91], v[144:147], v[216:219], v[88:91]
	v_mfma_f32_16x16x32_bf16 v[76:79], v[128:131], v[224:227], v[76:79]
	v_mfma_f32_16x16x32_bf16 v[72:75], v[144:147], v[224:227], v[72:75]
	v_mfma_f32_16x16x32_bf16 v[120:123], v[140:143], v[178:181], v[120:123]
	v_mfma_f32_16x16x32_bf16 v[124:127], v[148:151], v[178:181], v[124:127]
	v_mfma_f32_16x16x32_bf16 v[108:111], v[140:143], v[202:205], v[108:111]
	v_mfma_f32_16x16x32_bf16 v[104:107], v[148:151], v[202:205], v[104:107]
	v_mfma_f32_16x16x32_bf16 v[92:95], v[140:143], v[220:223], v[92:95]
	v_mfma_f32_16x16x32_bf16 v[88:91], v[148:151], v[220:223], v[88:91]
	v_mfma_f32_16x16x32_bf16 v[76:79], v[140:143], v[228:231], v[76:79]
	v_mfma_f32_16x16x32_bf16 v[72:75], v[148:151], v[228:231], v[72:75]
	s_setprio 0
	s_setprio 1
	v_mfma_f32_16x16x32_bf16 v[116:119], v[152:155], v[174:177], v[116:119]
	v_mfma_f32_16x16x32_bf16 v[112:115], v[160:163], v[174:177], v[112:115]
	v_mfma_f32_16x16x32_bf16 v[100:103], v[152:155], v[182:185], v[100:103]
	v_mfma_f32_16x16x32_bf16 v[96:99], v[160:163], v[182:185], v[96:99]
	v_mfma_f32_16x16x32_bf16 v[84:87], v[152:155], v[216:219], v[84:87]
	v_mfma_f32_16x16x32_bf16 v[80:83], v[160:163], v[216:219], v[80:83]
	v_mfma_f32_16x16x32_bf16 v[68:71], v[152:155], v[224:227], v[68:71]
	v_mfma_f32_16x16x32_bf16 v[64:67], v[160:163], v[224:227], v[64:67]
	v_mfma_f32_16x16x32_bf16 v[116:119], v[156:159], v[178:181], v[116:119]
	v_mfma_f32_16x16x32_bf16 v[112:115], v[170:173], v[178:181], v[112:115]
	v_mfma_f32_16x16x32_bf16 v[100:103], v[156:159], v[202:205], v[100:103]
	v_mfma_f32_16x16x32_bf16 v[96:99], v[170:173], v[202:205], v[96:99]
	v_mfma_f32_16x16x32_bf16 v[84:87], v[156:159], v[220:223], v[84:87]
	v_mfma_f32_16x16x32_bf16 v[80:83], v[170:173], v[220:223], v[80:83]
	v_mfma_f32_16x16x32_bf16 v[68:71], v[156:159], v[228:231], v[68:71]
	v_mfma_f32_16x16x32_bf16 v[64:67], v[170:173], v[228:231], v[64:67]
	s_setprio 0
	s_barrier
	s_add_i32 s20, s52, s55
	v_lshl_add_u64 v[164:165], s[40:41], 0, v[134:135]
	s_mov_b32 m0, s20
	ds_read_b128 v[174:177], v169 offset:16384
	ds_read_b128 v[178:181], v169 offset:17408
	ds_read_b128 v[182:185], v169 offset:18432
	ds_read_b128 v[202:205], v169 offset:19456
	ds_read_b128 v[216:219], v169 offset:20480
	ds_read_b128 v[220:223], v169 offset:21504
	ds_read_b128 v[224:227], v169 offset:22528
	ds_read_b128 v[228:231], v169 offset:23552
	global_load_lds_dwordx4 v[164:165], off
	s_add_i32 m0, s20, 0x2000
	s_add_u32 s20, s40, 0x40000
	v_lshl_add_u64 v[186:187], s[40:41], 0, v[132:133]
	s_addc_u32 s21, s41, 0
	s_add_i32 s52, s53, s55
	global_load_lds_dwordx4 v[186:187], off
	v_lshl_add_u64 v[194:195], s[20:21], 0, v[134:135]
	s_mov_b32 m0, s52
	v_lshl_add_u64 v[196:197], s[58:59], 0, v[132:133]
	global_load_lds_dwordx4 v[194:195], off
	v_lshl_add_u64 v[194:195], s[20:21], 0, v[132:133]
	s_add_i32 m0, s52, 0x2000
	s_nop 0
	global_load_lds_dwordx4 v[194:195], off
	v_lshl_add_u64 v[194:195], s[58:59], 0, v[134:135]
	s_mov_b32 m0, s46
	s_nop 0
	global_load_lds_dwordx4 v[194:195], off
	s_mov_b32 m0, s47
	s_nop 0
	global_load_lds_dwordx4 v[196:197], off
	s_waitcnt vmcnt(8)
	s_waitcnt lgkmcnt(0)
	s_barrier
	s_setprio 1
	s_waitcnt lgkmcnt(0)
	v_mfma_f32_16x16x32_bf16 v[60:63], v[128:131], v[174:177], v[60:63]
	v_mfma_f32_16x16x32_bf16 v[56:59], v[144:147], v[174:177], v[56:59]
	v_mfma_f32_16x16x32_bf16 v[44:47], v[128:131], v[182:185], v[44:47]
	v_mfma_f32_16x16x32_bf16 v[40:43], v[144:147], v[182:185], v[40:43]
	v_mfma_f32_16x16x32_bf16 v[28:31], v[128:131], v[216:219], v[28:31]
	v_mfma_f32_16x16x32_bf16 v[24:27], v[144:147], v[216:219], v[24:27]
	v_mfma_f32_16x16x32_bf16 v[12:15], v[128:131], v[224:227], v[12:15]
	v_mfma_f32_16x16x32_bf16 v[8:11], v[144:147], v[224:227], v[8:11]
	v_mfma_f32_16x16x32_bf16 v[60:63], v[140:143], v[178:181], v[60:63]
	v_mfma_f32_16x16x32_bf16 v[56:59], v[148:151], v[178:181], v[56:59]
	v_mfma_f32_16x16x32_bf16 v[44:47], v[140:143], v[202:205], v[44:47]
	v_mfma_f32_16x16x32_bf16 v[40:43], v[148:151], v[202:205], v[40:43]
	v_mfma_f32_16x16x32_bf16 v[28:31], v[140:143], v[220:223], v[28:31]
	v_mfma_f32_16x16x32_bf16 v[24:27], v[148:151], v[220:223], v[24:27]
	v_mfma_f32_16x16x32_bf16 v[12:15], v[140:143], v[228:231], v[12:15]
	v_mfma_f32_16x16x32_bf16 v[8:11], v[148:151], v[228:231], v[8:11]
	s_setprio 0
	s_setprio 1
	v_mfma_f32_16x16x32_bf16 v[52:55], v[152:155], v[174:177], v[52:55]
	v_mfma_f32_16x16x32_bf16 v[48:51], v[160:163], v[174:177], v[48:51]
	v_mfma_f32_16x16x32_bf16 v[36:39], v[152:155], v[182:185], v[36:39]
	v_mfma_f32_16x16x32_bf16 v[32:35], v[160:163], v[182:185], v[32:35]
	v_mfma_f32_16x16x32_bf16 v[20:23], v[152:155], v[216:219], v[20:23]
	v_mfma_f32_16x16x32_bf16 v[16:19], v[160:163], v[216:219], v[16:19]
	v_mfma_f32_16x16x32_bf16 v[4:7], v[152:155], v[224:227], v[4:7]
	v_mfma_f32_16x16x32_bf16 v[0:3], v[160:163], v[224:227], v[0:3]
	v_mfma_f32_16x16x32_bf16 v[52:55], v[156:159], v[178:181], v[52:55]
	v_mfma_f32_16x16x32_bf16 v[48:51], v[170:173], v[178:181], v[48:51]
	v_mfma_f32_16x16x32_bf16 v[36:39], v[156:159], v[202:205], v[36:39]
	v_mfma_f32_16x16x32_bf16 v[32:35], v[170:173], v[202:205], v[32:35]
	v_mfma_f32_16x16x32_bf16 v[20:23], v[156:159], v[220:223], v[20:23]
	v_mfma_f32_16x16x32_bf16 v[16:19], v[170:173], v[220:223], v[16:19]
	v_mfma_f32_16x16x32_bf16 v[4:7], v[156:159], v[228:231], v[4:7]
	v_mfma_f32_16x16x32_bf16 v[0:3], v[170:173], v[228:231], v[0:3]
	s_setprio 0
	s_barrier
	s_add_i32 s52, 0, 0x18000
	s_add_i32 s53, 0, 0x1c000
	s_add_u32 s20, s58, 0x40000
	s_addc_u32 s21, s59, 0
	s_mov_b32 m0, s25
	v_lshl_add_u64 v[244:245], s[20:21], 0, v[134:135]
	global_load_lds_dwordx4 v[244:245], off
	v_lshl_add_u64 v[246:247], s[20:21], 0, v[132:133]
	s_mov_b32 m0, s44
	s_nop 0
	global_load_lds_dwordx4 v[246:247], off
	v_add_u32_e32 v148, s52, v168
	v_add_u32_e32 v170, s53, v168
	ds_read_b128 v[128:131], v148
	ds_read_b128 v[140:143], v148 offset:1024
	ds_read_b128 v[144:147], v148 offset:2048
	ds_read_b128 v[148:151], v148 offset:3072
	ds_read_b128 v[152:155], v170
	ds_read_b128 v[156:159], v170 offset:1024
	ds_read_b128 v[160:163], v170 offset:2048
	ds_read_b128 v[170:173], v170 offset:3072
	ds_read_b128 v[174:177], v169 offset:32768
	ds_read_b128 v[178:181], v169 offset:33792
	ds_read_b128 v[182:185], v169 offset:34816
	ds_read_b128 v[202:205], v169 offset:35840
	ds_read_b128 v[216:219], v169 offset:36864
	ds_read_b128 v[220:223], v169 offset:37888
	ds_read_b128 v[224:227], v169 offset:38912
	ds_read_b128 v[228:231], v169 offset:39936
	s_waitcnt vmcnt(8)
	s_waitcnt lgkmcnt(0)


	s_barrier
	s_setprio 1
	s_waitcnt lgkmcnt(0)
	v_mfma_f32_16x16x32_bf16 v[120:123], v[128:131], v[174:177], v[120:123]
	v_mfma_f32_16x16x32_bf16 v[124:127], v[144:147], v[174:177], v[124:127]
	v_mfma_f32_16x16x32_bf16 v[108:111], v[128:131], v[182:185], v[108:111]
	v_mfma_f32_16x16x32_bf16 v[104:107], v[144:147], v[182:185], v[104:107]
	v_mfma_f32_16x16x32_bf16 v[92:95], v[128:131], v[216:219], v[92:95]
	v_mfma_f32_16x16x32_bf16 v[88:91], v[144:147], v[216:219], v[88:91]
	v_mfma_f32_16x16x32_bf16 v[76:79], v[128:131], v[224:227], v[76:79]
	v_mfma_f32_16x16x32_bf16 v[72:75], v[144:147], v[224:227], v[72:75]
	v_mfma_f32_16x16x32_bf16 v[120:123], v[140:143], v[178:181], v[120:123]
	v_mfma_f32_16x16x32_bf16 v[124:127], v[148:151], v[178:181], v[124:127]
	v_mfma_f32_16x16x32_bf16 v[108:111], v[140:143], v[202:205], v[108:111]
	v_mfma_f32_16x16x32_bf16 v[104:107], v[148:151], v[202:205], v[104:107]
	v_mfma_f32_16x16x32_bf16 v[92:95], v[140:143], v[220:223], v[92:95]
	v_mfma_f32_16x16x32_bf16 v[88:91], v[148:151], v[220:223], v[88:91]
	v_mfma_f32_16x16x32_bf16 v[76:79], v[140:143], v[228:231], v[76:79]
	v_mfma_f32_16x16x32_bf16 v[72:75], v[148:151], v[228:231], v[72:75]
	s_setprio 0
	s_setprio 1
	v_mfma_f32_16x16x32_bf16 v[116:119], v[152:155], v[174:177], v[116:119]
	v_mfma_f32_16x16x32_bf16 v[112:115], v[160:163], v[174:177], v[112:115]
	v_mfma_f32_16x16x32_bf16 v[100:103], v[152:155], v[182:185], v[100:103]
	v_mfma_f32_16x16x32_bf16 v[96:99], v[160:163], v[182:185], v[96:99]
	v_mfma_f32_16x16x32_bf16 v[84:87], v[152:155], v[216:219], v[84:87]
	v_mfma_f32_16x16x32_bf16 v[80:83], v[160:163], v[216:219], v[80:83]
	v_mfma_f32_16x16x32_bf16 v[68:71], v[152:155], v[224:227], v[68:71]
	v_mfma_f32_16x16x32_bf16 v[64:67], v[160:163], v[224:227], v[64:67]
	v_mfma_f32_16x16x32_bf16 v[116:119], v[156:159], v[178:181], v[116:119]
	v_mfma_f32_16x16x32_bf16 v[112:115], v[170:173], v[178:181], v[112:115]
	v_mfma_f32_16x16x32_bf16 v[100:103], v[156:159], v[202:205], v[100:103]
	v_mfma_f32_16x16x32_bf16 v[96:99], v[170:173], v[202:205], v[96:99]
	v_mfma_f32_16x16x32_bf16 v[84:87], v[156:159], v[220:223], v[84:87]
	v_mfma_f32_16x16x32_bf16 v[80:83], v[170:173], v[220:223], v[80:83]
	v_mfma_f32_16x16x32_bf16 v[68:71], v[156:159], v[228:231], v[68:71]
	v_mfma_f32_16x16x32_bf16 v[64:67], v[170:173], v[228:231], v[64:67]
	s_setprio 0
	s_barrier
	s_add_i32 s20, s52, s55
	v_lshl_add_u64 v[164:165], v[164:165], 0, s[62:63]
	s_mov_b32 m0, s20
	ds_read_b128 v[174:177], v169 offset:49152
	ds_read_b128 v[178:181], v169 offset:50176
	ds_read_b128 v[182:185], v169 offset:51200
	ds_read_b128 v[202:205], v169 offset:52224
	ds_read_b128 v[216:219], v169 offset:53248
	ds_read_b128 v[220:223], v169 offset:54272
	ds_read_b128 v[224:227], v169 offset:55296
	ds_read_b128 v[228:231], v169 offset:56320
	global_load_lds_dwordx4 v[164:165], off
	s_add_i32 m0, s20, 0x2000
	s_add_u32 s20, s40, 0x40080
	v_lshl_add_u64 v[164:165], v[186:187], 0, s[62:63]
	s_addc_u32 s21, s41, 0
	s_add_i32 s40, s53, s55
	global_load_lds_dwordx4 v[164:165], off
	v_lshl_add_u64 v[164:165], s[20:21], 0, v[134:135]
	s_mov_b32 m0, s40
	s_nop 0
	global_load_lds_dwordx4 v[164:165], off
	v_lshl_add_u64 v[164:165], s[20:21], 0, v[132:133]
	s_add_i32 m0, s40, 0x2000
	s_nop 0
	global_load_lds_dwordx4 v[164:165], off
	v_lshl_add_u64 v[164:165], v[194:195], 0, s[62:63]
	s_mov_b32 m0, s56
	s_nop 0
	global_load_lds_dwordx4 v[164:165], off
	v_lshl_add_u64 v[164:165], v[196:197], 0, s[62:63]
	s_mov_b32 m0, s57
	s_nop 0
	global_load_lds_dwordx4 v[164:165], off
	s_waitcnt vmcnt(8)
	s_waitcnt lgkmcnt(0)
	s_barrier
	s_setprio 1
	s_waitcnt lgkmcnt(0)
	v_mfma_f32_16x16x32_bf16 v[60:63], v[128:131], v[174:177], v[60:63]
	v_mfma_f32_16x16x32_bf16 v[56:59], v[144:147], v[174:177], v[56:59]
	v_mfma_f32_16x16x32_bf16 v[44:47], v[128:131], v[182:185], v[44:47]
	v_mfma_f32_16x16x32_bf16 v[40:43], v[144:147], v[182:185], v[40:43]
	v_mfma_f32_16x16x32_bf16 v[28:31], v[128:131], v[216:219], v[28:31]
	v_mfma_f32_16x16x32_bf16 v[24:27], v[144:147], v[216:219], v[24:27]
	v_mfma_f32_16x16x32_bf16 v[12:15], v[128:131], v[224:227], v[12:15]
	v_mfma_f32_16x16x32_bf16 v[8:11], v[144:147], v[224:227], v[8:11]
	v_mfma_f32_16x16x32_bf16 v[60:63], v[140:143], v[178:181], v[60:63]
	v_mfma_f32_16x16x32_bf16 v[56:59], v[148:151], v[178:181], v[56:59]
	v_mfma_f32_16x16x32_bf16 v[44:47], v[140:143], v[202:205], v[44:47]
	v_mfma_f32_16x16x32_bf16 v[40:43], v[148:151], v[202:205], v[40:43]
	v_mfma_f32_16x16x32_bf16 v[28:31], v[140:143], v[220:223], v[28:31]
	v_mfma_f32_16x16x32_bf16 v[24:27], v[148:151], v[220:223], v[24:27]
	v_mfma_f32_16x16x32_bf16 v[12:15], v[140:143], v[228:231], v[12:15]
	v_mfma_f32_16x16x32_bf16 v[8:11], v[148:151], v[228:231], v[8:11]
	s_setprio 0
	s_setprio 1
	v_mfma_f32_16x16x32_bf16 v[52:55], v[152:155], v[174:177], v[52:55]
	v_mfma_f32_16x16x32_bf16 v[48:51], v[160:163], v[174:177], v[48:51]
	v_mfma_f32_16x16x32_bf16 v[36:39], v[152:155], v[182:185], v[36:39]
	v_mfma_f32_16x16x32_bf16 v[32:35], v[160:163], v[182:185], v[32:35]
	v_mfma_f32_16x16x32_bf16 v[20:23], v[152:155], v[216:219], v[20:23]
	v_mfma_f32_16x16x32_bf16 v[16:19], v[160:163], v[216:219], v[16:19]
	v_mfma_f32_16x16x32_bf16 v[4:7], v[152:155], v[224:227], v[4:7]
	v_mfma_f32_16x16x32_bf16 v[0:3], v[160:163], v[224:227], v[0:3]
	v_mfma_f32_16x16x32_bf16 v[52:55], v[156:159], v[178:181], v[52:55]
	v_mfma_f32_16x16x32_bf16 v[48:51], v[170:173], v[178:181], v[48:51]
	v_mfma_f32_16x16x32_bf16 v[36:39], v[156:159], v[202:205], v[36:39]
	v_mfma_f32_16x16x32_bf16 v[32:35], v[170:173], v[202:205], v[32:35]
	v_mfma_f32_16x16x32_bf16 v[20:23], v[156:159], v[220:223], v[20:23]
	v_mfma_f32_16x16x32_bf16 v[16:19], v[170:173], v[220:223], v[16:19]
	v_mfma_f32_16x16x32_bf16 v[4:7], v[156:159], v[228:231], v[4:7]
	v_mfma_f32_16x16x32_bf16 v[0:3], v[170:173], v[228:231], v[0:3]
	s_setprio 0
	s_barrier
	s_add_u32 s38, s38, 0x100
	s_addc_u32 s39, s39, 0
	s_add_u32 s82, s82, 0x100
	s_addc_u32 s83, s83, 0
	s_cmp_ge_i32 s61, s80
	s_mov_b32 s40, s61
	s_cbranch_scc0 .LBB0_247

.LBB0_294:
	s_add_i32 vcc_lo, s82, 2
	s_add_u32 s20, s66, 0xfffc0080
	s_addc_u32 s21, s67, -1
	s_add_i32 vcc_hi, 0, 0x10000
	s_cmp_eq_u32 s60, s82
	s_cselect_b32 s87, s39, s21
	s_cselect_b32 s86, s41, s20
	v_add_u32_e32 v148, vcc_hi, v151
	s_cselect_b32 s83, s88, s95
	s_cselect_b32 s82, s89, s94
	v_lshl_add_u64 v[244:245], s[66:67], 0, v[136:137]
	s_add_i32 m0, s13, 0xc000
	s_nop 0
	global_load_lds_dwordx4 v[244:245], off
	v_lshl_add_u64 v[246:247], s[66:67], 0, v[138:139]
	s_add_i32 m0, s13, 0xe000
	s_nop 0
	global_load_lds_dwordx4 v[246:247], off
	s_add_i32 s52, 0, 0x14000
	ds_read_b128 v[140:143], v148
	ds_read_b128 v[144:147], v148 offset:1024
	ds_read_b128 v[154:157], v148 offset:2048
	ds_read_b128 v[158:161], v148 offset:3072
	v_add_u32_e32 v148, s52, v151
	ds_read_b128 v[162:165], v148
	ds_read_b128 v[166:169], v148 offset:1024
	ds_read_b128 v[170:173], v148 offset:2048
	ds_read_b128 v[174:177], v148 offset:3072
	ds_read_b128 v[178:181], v152
	ds_read_b128 v[182:185], v152 offset:1024
	ds_read_b128 v[202:205], v152 offset:2048
	ds_read_b128 v[216:219], v152 offset:3072
	ds_read_b128 v[220:223], v152 offset:4096
	ds_read_b128 v[224:227], v152 offset:5120
	ds_read_b128 v[228:231], v152 offset:6144
	ds_read_b128 v[232:235], v152 offset:7168
	s_waitcnt vmcnt(8)
	s_waitcnt lgkmcnt(0)


	s_barrier
	s_setprio 1
	s_waitcnt lgkmcnt(0)
	v_mfma_f32_16x16x32_bf16 v[120:123], v[140:143], v[178:181], v[120:123]
	v_mfma_f32_16x16x32_bf16 v[124:127], v[154:157], v[178:181], v[124:127]
	v_mfma_f32_16x16x32_bf16 v[108:111], v[140:143], v[202:205], v[108:111]
	v_mfma_f32_16x16x32_bf16 v[104:107], v[154:157], v[202:205], v[104:107]
	v_mfma_f32_16x16x32_bf16 v[92:95], v[140:143], v[220:223], v[92:95]
	v_mfma_f32_16x16x32_bf16 v[88:91], v[154:157], v[220:223], v[88:91]
	v_mfma_f32_16x16x32_bf16 v[76:79], v[140:143], v[228:231], v[76:79]
	v_mfma_f32_16x16x32_bf16 v[72:75], v[154:157], v[228:231], v[72:75]
	v_mfma_f32_16x16x32_bf16 v[120:123], v[144:147], v[182:185], v[120:123]
	v_mfma_f32_16x16x32_bf16 v[124:127], v[158:161], v[182:185], v[124:127]
	v_mfma_f32_16x16x32_bf16 v[108:111], v[144:147], v[216:219], v[108:111]
	v_mfma_f32_16x16x32_bf16 v[104:107], v[158:161], v[216:219], v[104:107]
	v_mfma_f32_16x16x32_bf16 v[92:95], v[144:147], v[224:227], v[92:95]
	v_mfma_f32_16x16x32_bf16 v[88:91], v[158:161], v[224:227], v[88:91]
	v_mfma_f32_16x16x32_bf16 v[76:79], v[144:147], v[232:235], v[76:79]
	v_mfma_f32_16x16x32_bf16 v[72:75], v[158:161], v[232:235], v[72:75]
	s_setprio 0
	s_setprio 1
	v_mfma_f32_16x16x32_bf16 v[116:119], v[162:165], v[178:181], v[116:119]
	v_mfma_f32_16x16x32_bf16 v[112:115], v[170:173], v[178:181], v[112:115]
	v_mfma_f32_16x16x32_bf16 v[100:103], v[162:165], v[202:205], v[100:103]
	v_mfma_f32_16x16x32_bf16 v[96:99], v[170:173], v[202:205], v[96:99]
	v_mfma_f32_16x16x32_bf16 v[84:87], v[162:165], v[220:223], v[84:87]
	v_mfma_f32_16x16x32_bf16 v[80:83], v[170:173], v[220:223], v[80:83]
	v_mfma_f32_16x16x32_bf16 v[68:71], v[162:165], v[228:231], v[68:71]
	v_mfma_f32_16x16x32_bf16 v[64:67], v[170:173], v[228:231], v[64:67]
	v_mfma_f32_16x16x32_bf16 v[116:119], v[166:169], v[182:185], v[116:119]
	v_mfma_f32_16x16x32_bf16 v[112:115], v[174:177], v[182:185], v[112:115]
	v_mfma_f32_16x16x32_bf16 v[100:103], v[166:169], v[216:219], v[100:103]
	v_mfma_f32_16x16x32_bf16 v[96:99], v[174:177], v[216:219], v[96:99]
	v_mfma_f32_16x16x32_bf16 v[84:87], v[166:169], v[224:227], v[84:87]
	v_mfma_f32_16x16x32_bf16 v[80:83], v[174:177], v[224:227], v[80:83]
	v_mfma_f32_16x16x32_bf16 v[68:71], v[166:169], v[232:235], v[68:71]
	v_mfma_f32_16x16x32_bf16 v[64:67], v[174:177], v[232:235], v[64:67]
	s_setprio 0
	s_barrier
	s_add_i32 s20, vcc_hi, s12
	v_lshl_add_u64 v[186:187], s[82:83], 0, v[132:133]
	s_mov_b32 m0, s20
	ds_read_b128 v[178:181], v152 offset:16384
	ds_read_b128 v[182:185], v152 offset:17408
	ds_read_b128 v[202:205], v152 offset:18432
	ds_read_b128 v[216:219], v152 offset:19456
	ds_read_b128 v[220:223], v152 offset:20480
	ds_read_b128 v[224:227], v152 offset:21504
	ds_read_b128 v[228:231], v152 offset:22528
	ds_read_b128 v[232:235], v152 offset:23552
	global_load_lds_dwordx4 v[186:187], off
	s_add_i32 m0, s20, 0x2000
	s_add_u32 s20, s82, 0x40000
	v_lshl_add_u64 v[194:195], s[82:83], 0, v[128:129]
	s_addc_u32 s21, s83, 0
	s_add_i32 s52, s52, s12
	global_load_lds_dwordx4 v[194:195], off
	v_lshl_add_u64 v[196:197], s[20:21], 0, v[132:133]
	s_mov_b32 m0, s52
	v_lshl_add_u64 v[236:237], s[86:87], 0, v[130:131]
	global_load_lds_dwordx4 v[196:197], off
	v_lshl_add_u64 v[196:197], s[20:21], 0, v[128:129]
	s_add_i32 m0, s52, 0x2000
	s_nop 0
	global_load_lds_dwordx4 v[196:197], off
	v_lshl_add_u64 v[196:197], s[86:87], 0, v[134:135]
	s_mov_b32 m0, s13
	s_nop 0
	global_load_lds_dwordx4 v[196:197], off
	s_mov_b32 m0, s28
	s_nop 0
	global_load_lds_dwordx4 v[236:237], off
	s_waitcnt vmcnt(8)
	s_waitcnt lgkmcnt(0)
	s_barrier
	s_setprio 1
	s_waitcnt lgkmcnt(0)
	v_mfma_f32_16x16x32_bf16 v[60:63], v[140:143], v[178:181], v[60:63]
	v_mfma_f32_16x16x32_bf16 v[56:59], v[154:157], v[178:181], v[56:59]
	v_mfma_f32_16x16x32_bf16 v[44:47], v[140:143], v[202:205], v[44:47]
	v_mfma_f32_16x16x32_bf16 v[40:43], v[154:157], v[202:205], v[40:43]
	v_mfma_f32_16x16x32_bf16 v[28:31], v[140:143], v[220:223], v[28:31]
	v_mfma_f32_16x16x32_bf16 v[24:27], v[154:157], v[220:223], v[24:27]
	v_mfma_f32_16x16x32_bf16 v[12:15], v[140:143], v[228:231], v[12:15]
	v_mfma_f32_16x16x32_bf16 v[8:11], v[154:157], v[228:231], v[8:11]
	v_mfma_f32_16x16x32_bf16 v[60:63], v[144:147], v[182:185], v[60:63]
	v_mfma_f32_16x16x32_bf16 v[56:59], v[158:161], v[182:185], v[56:59]
	v_mfma_f32_16x16x32_bf16 v[44:47], v[144:147], v[216:219], v[44:47]
	v_mfma_f32_16x16x32_bf16 v[40:43], v[158:161], v[216:219], v[40:43]
	v_mfma_f32_16x16x32_bf16 v[28:31], v[144:147], v[224:227], v[28:31]
	v_mfma_f32_16x16x32_bf16 v[24:27], v[158:161], v[224:227], v[24:27]
	v_mfma_f32_16x16x32_bf16 v[12:15], v[144:147], v[232:235], v[12:15]
	v_mfma_f32_16x16x32_bf16 v[8:11], v[158:161], v[232:235], v[8:11]
	s_setprio 0
	s_setprio 1
	v_mfma_f32_16x16x32_bf16 v[52:55], v[162:165], v[178:181], v[52:55]
	v_mfma_f32_16x16x32_bf16 v[48:51], v[170:173], v[178:181], v[48:51]
	v_mfma_f32_16x16x32_bf16 v[36:39], v[162:165], v[202:205], v[36:39]
	v_mfma_f32_16x16x32_bf16 v[32:35], v[170:173], v[202:205], v[32:35]
	v_mfma_f32_16x16x32_bf16 v[20:23], v[162:165], v[220:223], v[20:23]
	v_mfma_f32_16x16x32_bf16 v[16:19], v[170:173], v[220:223], v[16:19]
	v_mfma_f32_16x16x32_bf16 v[4:7], v[162:165], v[228:231], v[4:7]
	v_mfma_f32_16x16x32_bf16 v[0:3], v[170:173], v[228:231], v[0:3]
	v_mfma_f32_16x16x32_bf16 v[52:55], v[166:169], v[182:185], v[52:55]
	v_mfma_f32_16x16x32_bf16 v[48:51], v[174:177], v[182:185], v[48:51]
	v_mfma_f32_16x16x32_bf16 v[36:39], v[166:169], v[216:219], v[36:39]
	v_mfma_f32_16x16x32_bf16 v[32:35], v[174:177], v[216:219], v[32:35]
	v_mfma_f32_16x16x32_bf16 v[20:23], v[166:169], v[224:227], v[20:23]
	v_mfma_f32_16x16x32_bf16 v[16:19], v[174:177], v[224:227], v[16:19]
	v_mfma_f32_16x16x32_bf16 v[4:7], v[166:169], v[232:235], v[4:7]
	v_mfma_f32_16x16x32_bf16 v[0:3], v[174:177], v[232:235], v[0:3]
	s_setprio 0
	s_barrier
	s_add_i32 s52, 0, 0x18000
	s_add_u32 s20, s86, 0x40000
	s_addc_u32 s21, s87, 0
	s_mov_b32 m0, s46
	v_lshl_add_u64 v[244:245], s[20:21], 0, v[134:135]
	global_load_lds_dwordx4 v[244:245], off
	v_lshl_add_u64 v[246:247], s[20:21], 0, v[130:131]
	s_mov_b32 m0, s47
	s_nop 0
	global_load_lds_dwordx4 v[246:247], off
	v_add_u32_e32 v148, s52, v151
	s_add_i32 s53, 0, 0x1c000
	ds_read_b128 v[140:143], v148
	ds_read_b128 v[144:147], v148 offset:1024
	ds_read_b128 v[154:157], v148 offset:2048
	ds_read_b128 v[158:161], v148 offset:3072
	v_add_u32_e32 v148, s53, v151
	ds_read_b128 v[162:165], v148
	ds_read_b128 v[166:169], v148 offset:1024
	ds_read_b128 v[170:173], v148 offset:2048
	ds_read_b128 v[174:177], v148 offset:3072
	ds_read_b128 v[178:181], v152 offset:32768
	ds_read_b128 v[182:185], v152 offset:33792
	ds_read_b128 v[202:205], v152 offset:34816
	ds_read_b128 v[216:219], v152 offset:35840
	ds_read_b128 v[220:223], v152 offset:36864
	ds_read_b128 v[224:227], v152 offset:37888
	ds_read_b128 v[228:231], v152 offset:38912
	ds_read_b128 v[232:235], v152 offset:39936
	s_waitcnt vmcnt(8)
	s_waitcnt lgkmcnt(0)


	s_barrier
	s_setprio 1
	s_waitcnt lgkmcnt(0)
	v_mfma_f32_16x16x32_bf16 v[120:123], v[140:143], v[178:181], v[120:123]
	v_mfma_f32_16x16x32_bf16 v[124:127], v[154:157], v[178:181], v[124:127]
	v_mfma_f32_16x16x32_bf16 v[108:111], v[140:143], v[202:205], v[108:111]
	v_mfma_f32_16x16x32_bf16 v[104:107], v[154:157], v[202:205], v[104:107]
	v_mfma_f32_16x16x32_bf16 v[92:95], v[140:143], v[220:223], v[92:95]
	v_mfma_f32_16x16x32_bf16 v[88:91], v[154:157], v[220:223], v[88:91]
	v_mfma_f32_16x16x32_bf16 v[76:79], v[140:143], v[228:231], v[76:79]
	v_mfma_f32_16x16x32_bf16 v[72:75], v[154:157], v[228:231], v[72:75]
	v_mfma_f32_16x16x32_bf16 v[120:123], v[144:147], v[182:185], v[120:123]
	v_mfma_f32_16x16x32_bf16 v[124:127], v[158:161], v[182:185], v[124:127]
	v_mfma_f32_16x16x32_bf16 v[108:111], v[144:147], v[216:219], v[108:111]
	v_mfma_f32_16x16x32_bf16 v[104:107], v[158:161], v[216:219], v[104:107]
	v_mfma_f32_16x16x32_bf16 v[92:95], v[144:147], v[224:227], v[92:95]
	v_mfma_f32_16x16x32_bf16 v[88:91], v[158:161], v[224:227], v[88:91]
	v_mfma_f32_16x16x32_bf16 v[76:79], v[144:147], v[232:235], v[76:79]
	v_mfma_f32_16x16x32_bf16 v[72:75], v[158:161], v[232:235], v[72:75]
	s_setprio 0
	s_setprio 1
	v_mfma_f32_16x16x32_bf16 v[116:119], v[162:165], v[178:181], v[116:119]
	v_mfma_f32_16x16x32_bf16 v[112:115], v[170:173], v[178:181], v[112:115]
	v_mfma_f32_16x16x32_bf16 v[100:103], v[162:165], v[202:205], v[100:103]
	v_mfma_f32_16x16x32_bf16 v[96:99], v[170:173], v[202:205], v[96:99]
	v_mfma_f32_16x16x32_bf16 v[84:87], v[162:165], v[220:223], v[84:87]
	v_mfma_f32_16x16x32_bf16 v[80:83], v[170:173], v[220:223], v[80:83]
	v_mfma_f32_16x16x32_bf16 v[68:71], v[162:165], v[228:231], v[68:71]
	v_mfma_f32_16x16x32_bf16 v[64:67], v[170:173], v[228:231], v[64:67]
	v_mfma_f32_16x16x32_bf16 v[116:119], v[166:169], v[182:185], v[116:119]
	v_mfma_f32_16x16x32_bf16 v[112:115], v[174:177], v[182:185], v[112:115]
	v_mfma_f32_16x16x32_bf16 v[100:103], v[166:169], v[216:219], v[100:103]
	v_mfma_f32_16x16x32_bf16 v[96:99], v[174:177], v[216:219], v[96:99]
	v_mfma_f32_16x16x32_bf16 v[84:87], v[166:169], v[224:227], v[84:87]
	v_mfma_f32_16x16x32_bf16 v[80:83], v[174:177], v[224:227], v[80:83]
	v_mfma_f32_16x16x32_bf16 v[68:71], v[166:169], v[232:235], v[68:71]
	v_mfma_f32_16x16x32_bf16 v[64:67], v[174:177], v[232:235], v[64:67]
	s_setprio 0
	s_barrier
	s_add_i32 s20, s52, s12
	v_lshl_add_u64 v[186:187], v[186:187], 0, s[62:63]
	s_mov_b32 m0, s20
	ds_read_b128 v[178:181], v152 offset:49152
	ds_read_b128 v[182:185], v152 offset:50176
	ds_read_b128 v[202:205], v152 offset:51200
	ds_read_b128 v[216:219], v152 offset:52224
	ds_read_b128 v[220:223], v152 offset:53248
	ds_read_b128 v[224:227], v152 offset:54272
	ds_read_b128 v[228:231], v152 offset:55296
	ds_read_b128 v[232:235], v152 offset:56320
	global_load_lds_dwordx4 v[186:187], off
	s_add_i32 m0, s20, 0x2000
	s_add_u32 s20, s82, 0x40080
	v_lshl_add_u64 v[186:187], v[194:195], 0, s[62:63]
	s_addc_u32 s21, s83, 0
	s_add_i32 s52, s53, s12
	global_load_lds_dwordx4 v[186:187], off
	v_lshl_add_u64 v[186:187], s[20:21], 0, v[132:133]
	s_mov_b32 m0, s52
	s_nop 0
	global_load_lds_dwordx4 v[186:187], off
	v_lshl_add_u64 v[186:187], s[20:21], 0, v[128:129]
	s_add_i32 m0, s52, 0x2000
	s_nop 0
	global_load_lds_dwordx4 v[186:187], off
	v_lshl_add_u64 v[186:187], v[196:197], 0, s[62:63]
	s_mov_b32 m0, s48
	s_nop 0
	global_load_lds_dwordx4 v[186:187], off
	v_lshl_add_u64 v[186:187], v[236:237], 0, s[62:63]
	s_mov_b32 m0, s49
	s_nop 0
	global_load_lds_dwordx4 v[186:187], off
	s_waitcnt vmcnt(8)
	s_waitcnt lgkmcnt(0)
	s_barrier
	s_setprio 1
	s_waitcnt lgkmcnt(0)
	v_mfma_f32_16x16x32_bf16 v[60:63], v[140:143], v[178:181], v[60:63]
	v_mfma_f32_16x16x32_bf16 v[56:59], v[154:157], v[178:181], v[56:59]
	v_mfma_f32_16x16x32_bf16 v[44:47], v[140:143], v[202:205], v[44:47]
	v_mfma_f32_16x16x32_bf16 v[40:43], v[154:157], v[202:205], v[40:43]
	v_mfma_f32_16x16x32_bf16 v[28:31], v[140:143], v[220:223], v[28:31]
	v_mfma_f32_16x16x32_bf16 v[24:27], v[154:157], v[220:223], v[24:27]
	v_mfma_f32_16x16x32_bf16 v[12:15], v[140:143], v[228:231], v[12:15]
	v_mfma_f32_16x16x32_bf16 v[8:11], v[154:157], v[228:231], v[8:11]
	v_mfma_f32_16x16x32_bf16 v[60:63], v[144:147], v[182:185], v[60:63]
	v_mfma_f32_16x16x32_bf16 v[56:59], v[158:161], v[182:185], v[56:59]
	v_mfma_f32_16x16x32_bf16 v[44:47], v[144:147], v[216:219], v[44:47]
	v_mfma_f32_16x16x32_bf16 v[40:43], v[158:161], v[216:219], v[40:43]
	v_mfma_f32_16x16x32_bf16 v[28:31], v[144:147], v[224:227], v[28:31]
	v_mfma_f32_16x16x32_bf16 v[24:27], v[158:161], v[224:227], v[24:27]
	v_mfma_f32_16x16x32_bf16 v[12:15], v[144:147], v[232:235], v[12:15]
	v_mfma_f32_16x16x32_bf16 v[8:11], v[158:161], v[232:235], v[8:11]
	s_setprio 0
	s_setprio 1
	v_mfma_f32_16x16x32_bf16 v[52:55], v[162:165], v[178:181], v[52:55]
	v_mfma_f32_16x16x32_bf16 v[48:51], v[170:173], v[178:181], v[48:51]
	v_mfma_f32_16x16x32_bf16 v[36:39], v[162:165], v[202:205], v[36:39]
	v_mfma_f32_16x16x32_bf16 v[32:35], v[170:173], v[202:205], v[32:35]
	v_mfma_f32_16x16x32_bf16 v[20:23], v[162:165], v[220:223], v[20:23]
	v_mfma_f32_16x16x32_bf16 v[16:19], v[170:173], v[220:223], v[16:19]
	v_mfma_f32_16x16x32_bf16 v[4:7], v[162:165], v[228:231], v[4:7]
	v_mfma_f32_16x16x32_bf16 v[0:3], v[170:173], v[228:231], v[0:3]
	v_mfma_f32_16x16x32_bf16 v[52:55], v[166:169], v[182:185], v[52:55]
	v_mfma_f32_16x16x32_bf16 v[48:51], v[174:177], v[182:185], v[48:51]
	v_mfma_f32_16x16x32_bf16 v[36:39], v[166:169], v[216:219], v[36:39]
	v_mfma_f32_16x16x32_bf16 v[32:35], v[174:177], v[216:219], v[32:35]
	v_mfma_f32_16x16x32_bf16 v[20:23], v[166:169], v[224:227], v[20:23]
	v_mfma_f32_16x16x32_bf16 v[16:19], v[174:177], v[224:227], v[16:19]
	v_mfma_f32_16x16x32_bf16 v[4:7], v[166:169], v[232:235], v[4:7]
	v_mfma_f32_16x16x32_bf16 v[0:3], v[174:177], v[232:235], v[0:3]
	s_setprio 0
	s_barrier
	s_add_u32 s66, s66, 0x100
	s_addc_u32 s67, s67, 0
	s_add_u32 s94, s94, 0x100
	s_addc_u32 s95, s95, 0
	s_cmp_ge_i32 vcc_lo, s55
	s_mov_b32 s82, vcc_lo
	s_cbranch_scc0 .LBB0_294
	s_mov_b64 s[88:89], 0x8000

.LBB0_316:
	s_add_i32 vcc_lo, s82, 2
	s_add_u32 s20, s66, 0xfffc0080
	s_addc_u32 s21, s67, -1
	s_add_i32 s52, 0, 0x10000
	s_cmp_eq_u32 s60, s82
	s_cselect_b32 s87, s39, s21
	s_cselect_b32 s86, s41, s20
	s_cselect_b32 s83, s88, s95
	s_cselect_b32 s82, s89, s94
	s_add_i32 s53, 0, 0x14000
	v_lshl_add_u64 v[244:245], s[66:67], 0, v[136:137]
	s_add_i32 m0, s13, 0xc000
	s_nop 0
	global_load_lds_dwordx4 v[244:245], off
	v_lshl_add_u64 v[246:247], s[66:67], 0, v[138:139]
	s_add_i32 m0, s13, 0xe000
	s_nop 0
	global_load_lds_dwordx4 v[246:247], off
	v_add_u32_e32 v156, s52, v142
	v_add_u32_e32 v172, s53, v142
	ds_read_b128 v[144:147], v156
	ds_read_b128 v[148:151], v156 offset:1024
	ds_read_b128 v[152:155], v156 offset:2048
	ds_read_b128 v[156:159], v156 offset:3072
	ds_read_b128 v[160:163], v172
	ds_read_b128 v[164:167], v172 offset:1024
	ds_read_b128 v[168:171], v172 offset:2048
	ds_read_b128 v[172:175], v172 offset:3072
	ds_read_b128 v[176:179], v143
	ds_read_b128 v[180:183], v143 offset:1024
	ds_read_b128 v[184:187], v143 offset:2048
	ds_read_b128 v[202:205], v143 offset:3072
	ds_read_b128 v[216:219], v143 offset:4096
	ds_read_b128 v[220:223], v143 offset:5120
	ds_read_b128 v[224:227], v143 offset:6144
	ds_read_b128 v[228:231], v143 offset:7168
	s_waitcnt vmcnt(8)
	s_waitcnt lgkmcnt(0)


	s_barrier
	s_setprio 1
	s_waitcnt lgkmcnt(0)
	v_mfma_f32_16x16x32_bf16 v[124:127], v[144:147], v[176:179], v[124:127]
	v_mfma_f32_16x16x32_bf16 v[120:123], v[152:155], v[176:179], v[120:123]
	v_mfma_f32_16x16x32_bf16 v[108:111], v[144:147], v[184:187], v[108:111]
	v_mfma_f32_16x16x32_bf16 v[104:107], v[152:155], v[184:187], v[104:107]
	v_mfma_f32_16x16x32_bf16 v[92:95], v[144:147], v[216:219], v[92:95]
	v_mfma_f32_16x16x32_bf16 v[88:91], v[152:155], v[216:219], v[88:91]
	v_mfma_f32_16x16x32_bf16 v[76:79], v[144:147], v[224:227], v[76:79]
	v_mfma_f32_16x16x32_bf16 v[72:75], v[152:155], v[224:227], v[72:75]
	v_mfma_f32_16x16x32_bf16 v[124:127], v[148:151], v[180:183], v[124:127]
	v_mfma_f32_16x16x32_bf16 v[120:123], v[156:159], v[180:183], v[120:123]
	v_mfma_f32_16x16x32_bf16 v[108:111], v[148:151], v[202:205], v[108:111]
	v_mfma_f32_16x16x32_bf16 v[104:107], v[156:159], v[202:205], v[104:107]
	v_mfma_f32_16x16x32_bf16 v[92:95], v[148:151], v[220:223], v[92:95]
	v_mfma_f32_16x16x32_bf16 v[88:91], v[156:159], v[220:223], v[88:91]
	v_mfma_f32_16x16x32_bf16 v[76:79], v[148:151], v[228:231], v[76:79]
	v_mfma_f32_16x16x32_bf16 v[72:75], v[156:159], v[228:231], v[72:75]
	s_setprio 0
	s_setprio 1
	v_mfma_f32_16x16x32_bf16 v[116:119], v[160:163], v[176:179], v[116:119]
	v_mfma_f32_16x16x32_bf16 v[112:115], v[168:171], v[176:179], v[112:115]
	v_mfma_f32_16x16x32_bf16 v[100:103], v[160:163], v[184:187], v[100:103]
	v_mfma_f32_16x16x32_bf16 v[96:99], v[168:171], v[184:187], v[96:99]
	v_mfma_f32_16x16x32_bf16 v[84:87], v[160:163], v[216:219], v[84:87]
	v_mfma_f32_16x16x32_bf16 v[80:83], v[168:171], v[216:219], v[80:83]
	v_mfma_f32_16x16x32_bf16 v[68:71], v[160:163], v[224:227], v[68:71]
	v_mfma_f32_16x16x32_bf16 v[64:67], v[168:171], v[224:227], v[64:67]
	v_mfma_f32_16x16x32_bf16 v[116:119], v[164:167], v[180:183], v[116:119]
	v_mfma_f32_16x16x32_bf16 v[112:115], v[172:175], v[180:183], v[112:115]
	v_mfma_f32_16x16x32_bf16 v[100:103], v[164:167], v[202:205], v[100:103]
	v_mfma_f32_16x16x32_bf16 v[96:99], v[172:175], v[202:205], v[96:99]
	v_mfma_f32_16x16x32_bf16 v[84:87], v[164:167], v[220:223], v[84:87]
	v_mfma_f32_16x16x32_bf16 v[80:83], v[172:175], v[220:223], v[80:83]
	v_mfma_f32_16x16x32_bf16 v[68:71], v[164:167], v[228:231], v[68:71]
	v_mfma_f32_16x16x32_bf16 v[64:67], v[172:175], v[228:231], v[64:67]
	s_setprio 0
	s_barrier
	s_add_i32 s20, s52, s12
	v_lshl_add_u64 v[194:195], s[82:83], 0, v[132:133]
	s_mov_b32 m0, s20
	ds_read_b128 v[176:179], v143 offset:16384
	ds_read_b128 v[180:183], v143 offset:17408
	ds_read_b128 v[184:187], v143 offset:18432
	ds_read_b128 v[202:205], v143 offset:19456
	ds_read_b128 v[216:219], v143 offset:20480
	ds_read_b128 v[220:223], v143 offset:21504
	ds_read_b128 v[224:227], v143 offset:22528
	ds_read_b128 v[228:231], v143 offset:23552
	global_load_lds_dwordx4 v[194:195], off
	s_add_i32 m0, s20, 0x2000
	s_add_u32 s20, s82, 0x40000
	v_lshl_add_u64 v[196:197], s[82:83], 0, v[128:129]
	s_addc_u32 s21, s83, 0
	s_add_i32 s52, s53, s12
	global_load_lds_dwordx4 v[196:197], off
	v_lshl_add_u64 v[232:233], s[20:21], 0, v[132:133]
	s_mov_b32 m0, s52
	v_lshl_add_u64 v[234:235], s[86:87], 0, v[130:131]
	global_load_lds_dwordx4 v[232:233], off
	v_lshl_add_u64 v[232:233], s[20:21], 0, v[128:129]
	s_add_i32 m0, s52, 0x2000
	s_nop 0
	global_load_lds_dwordx4 v[232:233], off
	v_lshl_add_u64 v[232:233], s[86:87], 0, v[134:135]
	s_mov_b32 m0, s13
	s_nop 0
	global_load_lds_dwordx4 v[232:233], off
	s_mov_b32 m0, s28
	s_nop 0
	global_load_lds_dwordx4 v[234:235], off
	s_waitcnt vmcnt(8)
	s_waitcnt lgkmcnt(0)
	s_barrier
	s_setprio 1
	s_waitcnt lgkmcnt(0)
	v_mfma_f32_16x16x32_bf16 v[60:63], v[144:147], v[176:179], v[60:63]
	v_mfma_f32_16x16x32_bf16 v[56:59], v[152:155], v[176:179], v[56:59]
	v_mfma_f32_16x16x32_bf16 v[44:47], v[144:147], v[184:187], v[44:47]
	v_mfma_f32_16x16x32_bf16 v[40:43], v[152:155], v[184:187], v[40:43]
	v_mfma_f32_16x16x32_bf16 v[28:31], v[144:147], v[216:219], v[28:31]
	v_mfma_f32_16x16x32_bf16 v[24:27], v[152:155], v[216:219], v[24:27]
	v_mfma_f32_16x16x32_bf16 v[12:15], v[144:147], v[224:227], v[12:15]
	v_mfma_f32_16x16x32_bf16 v[8:11], v[152:155], v[224:227], v[8:11]
	v_mfma_f32_16x16x32_bf16 v[60:63], v[148:151], v[180:183], v[60:63]
	v_mfma_f32_16x16x32_bf16 v[56:59], v[156:159], v[180:183], v[56:59]
	v_mfma_f32_16x16x32_bf16 v[44:47], v[148:151], v[202:205], v[44:47]
	v_mfma_f32_16x16x32_bf16 v[40:43], v[156:159], v[202:205], v[40:43]
	v_mfma_f32_16x16x32_bf16 v[28:31], v[148:151], v[220:223], v[28:31]
	v_mfma_f32_16x16x32_bf16 v[24:27], v[156:159], v[220:223], v[24:27]
	v_mfma_f32_16x16x32_bf16 v[12:15], v[148:151], v[228:231], v[12:15]
	v_mfma_f32_16x16x32_bf16 v[8:11], v[156:159], v[228:231], v[8:11]
	s_setprio 0
	s_setprio 1
	v_mfma_f32_16x16x32_bf16 v[52:55], v[160:163], v[176:179], v[52:55]
	v_mfma_f32_16x16x32_bf16 v[48:51], v[168:171], v[176:179], v[48:51]
	v_mfma_f32_16x16x32_bf16 v[36:39], v[160:163], v[184:187], v[36:39]
	v_mfma_f32_16x16x32_bf16 v[32:35], v[168:171], v[184:187], v[32:35]
	v_mfma_f32_16x16x32_bf16 v[20:23], v[160:163], v[216:219], v[20:23]
	v_mfma_f32_16x16x32_bf16 v[16:19], v[168:171], v[216:219], v[16:19]
	v_mfma_f32_16x16x32_bf16 v[4:7], v[160:163], v[224:227], v[4:7]
	v_mfma_f32_16x16x32_bf16 v[0:3], v[168:171], v[224:227], v[0:3]
	v_mfma_f32_16x16x32_bf16 v[52:55], v[164:167], v[180:183], v[52:55]
	v_mfma_f32_16x16x32_bf16 v[48:51], v[172:175], v[180:183], v[48:51]
	v_mfma_f32_16x16x32_bf16 v[36:39], v[164:167], v[202:205], v[36:39]
	v_mfma_f32_16x16x32_bf16 v[32:35], v[172:175], v[202:205], v[32:35]
	v_mfma_f32_16x16x32_bf16 v[20:23], v[164:167], v[220:223], v[20:23]
	v_mfma_f32_16x16x32_bf16 v[16:19], v[172:175], v[220:223], v[16:19]
	v_mfma_f32_16x16x32_bf16 v[4:7], v[164:167], v[228:231], v[4:7]
	v_mfma_f32_16x16x32_bf16 v[0:3], v[172:175], v[228:231], v[0:3]
	s_setprio 0
	s_barrier
	s_add_i32 s52, 0, 0x18000
	s_add_i32 s53, 0, 0x1c000
	s_add_u32 s20, s86, 0x40000
	s_addc_u32 s21, s87, 0
	s_mov_b32 m0, s46
	v_lshl_add_u64 v[244:245], s[20:21], 0, v[134:135]
	global_load_lds_dwordx4 v[244:245], off
	v_lshl_add_u64 v[246:247], s[20:21], 0, v[130:131]
	s_mov_b32 m0, s47
	s_nop 0
	global_load_lds_dwordx4 v[246:247], off
	v_add_u32_e32 v156, s52, v142
	v_add_u32_e32 v172, s53, v142
	ds_read_b128 v[144:147], v156
	ds_read_b128 v[148:151], v156 offset:1024
	ds_read_b128 v[152:155], v156 offset:2048
	ds_read_b128 v[156:159], v156 offset:3072
	ds_read_b128 v[160:163], v172
	ds_read_b128 v[164:167], v172 offset:1024
	ds_read_b128 v[168:171], v172 offset:2048
	ds_read_b128 v[172:175], v172 offset:3072
	ds_read_b128 v[176:179], v143 offset:32768
	ds_read_b128 v[180:183], v143 offset:33792
	ds_read_b128 v[184:187], v143 offset:34816
	ds_read_b128 v[202:205], v143 offset:35840
	ds_read_b128 v[216:219], v143 offset:36864
	ds_read_b128 v[220:223], v143 offset:37888
	ds_read_b128 v[224:227], v143 offset:38912
	ds_read_b128 v[228:231], v143 offset:39936
	s_waitcnt vmcnt(8)
	s_waitcnt lgkmcnt(0)


	s_barrier
	s_setprio 1
	s_waitcnt lgkmcnt(0)
	v_mfma_f32_16x16x32_bf16 v[124:127], v[144:147], v[176:179], v[124:127]
	v_mfma_f32_16x16x32_bf16 v[120:123], v[152:155], v[176:179], v[120:123]
	v_mfma_f32_16x16x32_bf16 v[108:111], v[144:147], v[184:187], v[108:111]
	v_mfma_f32_16x16x32_bf16 v[104:107], v[152:155], v[184:187], v[104:107]
	v_mfma_f32_16x16x32_bf16 v[92:95], v[144:147], v[216:219], v[92:95]
	v_mfma_f32_16x16x32_bf16 v[88:91], v[152:155], v[216:219], v[88:91]
	v_mfma_f32_16x16x32_bf16 v[76:79], v[144:147], v[224:227], v[76:79]
	v_mfma_f32_16x16x32_bf16 v[72:75], v[152:155], v[224:227], v[72:75]
	v_mfma_f32_16x16x32_bf16 v[124:127], v[148:151], v[180:183], v[124:127]
	v_mfma_f32_16x16x32_bf16 v[120:123], v[156:159], v[180:183], v[120:123]
	v_mfma_f32_16x16x32_bf16 v[108:111], v[148:151], v[202:205], v[108:111]
	v_mfma_f32_16x16x32_bf16 v[104:107], v[156:159], v[202:205], v[104:107]
	v_mfma_f32_16x16x32_bf16 v[92:95], v[148:151], v[220:223], v[92:95]
	v_mfma_f32_16x16x32_bf16 v[88:91], v[156:159], v[220:223], v[88:91]
	v_mfma_f32_16x16x32_bf16 v[76:79], v[148:151], v[228:231], v[76:79]
	v_mfma_f32_16x16x32_bf16 v[72:75], v[156:159], v[228:231], v[72:75]
	s_setprio 0
	s_setprio 1
	v_mfma_f32_16x16x32_bf16 v[116:119], v[160:163], v[176:179], v[116:119]
	v_mfma_f32_16x16x32_bf16 v[112:115], v[168:171], v[176:179], v[112:115]
	v_mfma_f32_16x16x32_bf16 v[100:103], v[160:163], v[184:187], v[100:103]
	v_mfma_f32_16x16x32_bf16 v[96:99], v[168:171], v[184:187], v[96:99]
	v_mfma_f32_16x16x32_bf16 v[84:87], v[160:163], v[216:219], v[84:87]
	v_mfma_f32_16x16x32_bf16 v[80:83], v[168:171], v[216:219], v[80:83]
	v_mfma_f32_16x16x32_bf16 v[68:71], v[160:163], v[224:227], v[68:71]
	v_mfma_f32_16x16x32_bf16 v[64:67], v[168:171], v[224:227], v[64:67]
	v_mfma_f32_16x16x32_bf16 v[116:119], v[164:167], v[180:183], v[116:119]
	v_mfma_f32_16x16x32_bf16 v[112:115], v[172:175], v[180:183], v[112:115]
	v_mfma_f32_16x16x32_bf16 v[100:103], v[164:167], v[202:205], v[100:103]
	v_mfma_f32_16x16x32_bf16 v[96:99], v[172:175], v[202:205], v[96:99]
	v_mfma_f32_16x16x32_bf16 v[84:87], v[164:167], v[220:223], v[84:87]
	v_mfma_f32_16x16x32_bf16 v[80:83], v[172:175], v[220:223], v[80:83]
	v_mfma_f32_16x16x32_bf16 v[68:71], v[164:167], v[228:231], v[68:71]
	v_mfma_f32_16x16x32_bf16 v[64:67], v[172:175], v[228:231], v[64:67]
	s_setprio 0
	s_barrier
	s_add_i32 s20, s52, s12
	v_lshl_add_u64 v[194:195], v[194:195], 0, s[62:63]
	s_mov_b32 m0, s20
	ds_read_b128 v[176:179], v143 offset:49152
	ds_read_b128 v[180:183], v143 offset:50176
	ds_read_b128 v[184:187], v143 offset:51200
	ds_read_b128 v[202:205], v143 offset:52224
	ds_read_b128 v[216:219], v143 offset:53248
	ds_read_b128 v[220:223], v143 offset:54272
	ds_read_b128 v[224:227], v143 offset:55296
	ds_read_b128 v[228:231], v143 offset:56320
	global_load_lds_dwordx4 v[194:195], off
	s_add_i32 m0, s20, 0x2000
	s_add_u32 s20, s82, 0x40080
	v_lshl_add_u64 v[194:195], v[196:197], 0, s[62:63]
	s_addc_u32 s21, s83, 0
	s_add_i32 s52, s53, s12
	global_load_lds_dwordx4 v[194:195], off
	v_lshl_add_u64 v[194:195], s[20:21], 0, v[132:133]
	s_mov_b32 m0, s52
	s_nop 0
	global_load_lds_dwordx4 v[194:195], off
	v_lshl_add_u64 v[194:195], s[20:21], 0, v[128:129]
	s_add_i32 m0, s52, 0x2000
	s_nop 0
	global_load_lds_dwordx4 v[194:195], off
	v_lshl_add_u64 v[194:195], v[232:233], 0, s[62:63]
	s_mov_b32 m0, s56
	s_nop 0
	global_load_lds_dwordx4 v[194:195], off
	v_lshl_add_u64 v[194:195], v[234:235], 0, s[62:63]
	s_mov_b32 m0, s57
	s_nop 0
	global_load_lds_dwordx4 v[194:195], off
	s_waitcnt vmcnt(8)
	s_waitcnt lgkmcnt(0)
	s_barrier
	s_setprio 1
	s_waitcnt lgkmcnt(0)
	v_mfma_f32_16x16x32_bf16 v[60:63], v[144:147], v[176:179], v[60:63]
	v_mfma_f32_16x16x32_bf16 v[56:59], v[152:155], v[176:179], v[56:59]
	v_mfma_f32_16x16x32_bf16 v[44:47], v[144:147], v[184:187], v[44:47]
	v_mfma_f32_16x16x32_bf16 v[40:43], v[152:155], v[184:187], v[40:43]
	v_mfma_f32_16x16x32_bf16 v[28:31], v[144:147], v[216:219], v[28:31]
	v_mfma_f32_16x16x32_bf16 v[24:27], v[152:155], v[216:219], v[24:27]
	v_mfma_f32_16x16x32_bf16 v[12:15], v[144:147], v[224:227], v[12:15]
	v_mfma_f32_16x16x32_bf16 v[8:11], v[152:155], v[224:227], v[8:11]
	v_mfma_f32_16x16x32_bf16 v[60:63], v[148:151], v[180:183], v[60:63]
	v_mfma_f32_16x16x32_bf16 v[56:59], v[156:159], v[180:183], v[56:59]
	v_mfma_f32_16x16x32_bf16 v[44:47], v[148:151], v[202:205], v[44:47]
	v_mfma_f32_16x16x32_bf16 v[40:43], v[156:159], v[202:205], v[40:43]
	v_mfma_f32_16x16x32_bf16 v[28:31], v[148:151], v[220:223], v[28:31]
	v_mfma_f32_16x16x32_bf16 v[24:27], v[156:159], v[220:223], v[24:27]
	v_mfma_f32_16x16x32_bf16 v[12:15], v[148:151], v[228:231], v[12:15]
	v_mfma_f32_16x16x32_bf16 v[8:11], v[156:159], v[228:231], v[8:11]
	s_setprio 0
	s_setprio 1
	v_mfma_f32_16x16x32_bf16 v[52:55], v[160:163], v[176:179], v[52:55]
	v_mfma_f32_16x16x32_bf16 v[48:51], v[168:171], v[176:179], v[48:51]
	v_mfma_f32_16x16x32_bf16 v[36:39], v[160:163], v[184:187], v[36:39]
	v_mfma_f32_16x16x32_bf16 v[32:35], v[168:171], v[184:187], v[32:35]
	v_mfma_f32_16x16x32_bf16 v[20:23], v[160:163], v[216:219], v[20:23]
	v_mfma_f32_16x16x32_bf16 v[16:19], v[168:171], v[216:219], v[16:19]
	v_mfma_f32_16x16x32_bf16 v[4:7], v[160:163], v[224:227], v[4:7]
	v_mfma_f32_16x16x32_bf16 v[0:3], v[168:171], v[224:227], v[0:3]
	v_mfma_f32_16x16x32_bf16 v[52:55], v[164:167], v[180:183], v[52:55]
	v_mfma_f32_16x16x32_bf16 v[48:51], v[172:175], v[180:183], v[48:51]
	v_mfma_f32_16x16x32_bf16 v[36:39], v[164:167], v[202:205], v[36:39]
	v_mfma_f32_16x16x32_bf16 v[32:35], v[172:175], v[202:205], v[32:35]
	v_mfma_f32_16x16x32_bf16 v[20:23], v[164:167], v[220:223], v[20:23]
	v_mfma_f32_16x16x32_bf16 v[16:19], v[172:175], v[220:223], v[16:19]
	v_mfma_f32_16x16x32_bf16 v[4:7], v[164:167], v[228:231], v[4:7]
	v_mfma_f32_16x16x32_bf16 v[0:3], v[172:175], v[228:231], v[0:3]
	s_setprio 0
	s_barrier
	s_add_u32 s66, s66, 0x100
	s_addc_u32 s67, s67, 0
	s_add_u32 s94, s94, 0x100
	s_addc_u32 s95, s95, 0
	s_cmp_ge_i32 vcc_lo, s48
	s_mov_b32 s82, vcc_lo
	s_cbranch_scc0 .LBB0_316
	s_mov_b64 s[88:89], 0x8000

.LBB0_578:
	s_add_i32 s95, s42, 2
	s_add_u32 s43, s40, 0xfffc0080
	s_addc_u32 s56, s41, -1
	s_add_i32 vcc_lo, 0, 0x10000
	s_cmp_eq_u32 s87, s42
	s_cselect_b32 s57, s49, s56
	s_cselect_b32 s56, s51, s43
	s_cselect_b32 s43, s59, s94
	s_cselect_b32 s42, s88, s89
	s_add_i32 s36, 0, 0x14000
	v_lshl_add_u64 v[244:245], s[40:41], 0, v[142:143]
	s_add_i32 m0, s5, 0xc000
	s_nop 0
	global_load_lds_dwordx4 v[244:245], off
	v_lshl_add_u64 v[246:247], s[40:41], 0, v[144:145]
	s_add_i32 m0, s5, 0xe000
	s_nop 0
	global_load_lds_dwordx4 v[246:247], off
	v_add_u32_e32 v150, vcc_lo, v156
	v_add_u32_e32 v170, s36, v156
	ds_read_b128 v[128:131], v150
	ds_read_b128 v[132:135], v150 offset:1024
	ds_read_b128 v[146:149], v150 offset:2048
	ds_read_b128 v[150:153], v150 offset:3072
	ds_read_b128 v[158:161], v170
	ds_read_b128 v[162:165], v170 offset:1024
	ds_read_b128 v[166:169], v170 offset:2048
	ds_read_b128 v[170:173], v170 offset:3072
	ds_read_b128 v[174:177], v157
	ds_read_b128 v[178:181], v157 offset:1024
	ds_read_b128 v[182:185], v157 offset:2048
	ds_read_b128 v[194:197], v157 offset:3072
	ds_read_b128 v[202:205], v157 offset:4096
	ds_read_b128 v[216:219], v157 offset:5120
	ds_read_b128 v[220:223], v157 offset:6144
	ds_read_b128 v[224:227], v157 offset:7168
	s_waitcnt vmcnt(8)
	s_waitcnt lgkmcnt(0)


	s_barrier
	s_setprio 1
	s_waitcnt lgkmcnt(0)
	v_mfma_f32_16x16x32_bf16 v[124:127], v[128:131], v[174:177], v[124:127]
	v_mfma_f32_16x16x32_bf16 v[120:123], v[146:149], v[174:177], v[120:123]
	v_mfma_f32_16x16x32_bf16 v[108:111], v[128:131], v[182:185], v[108:111]
	v_mfma_f32_16x16x32_bf16 v[104:107], v[146:149], v[182:185], v[104:107]
	v_mfma_f32_16x16x32_bf16 v[92:95], v[128:131], v[202:205], v[92:95]
	v_mfma_f32_16x16x32_bf16 v[88:91], v[146:149], v[202:205], v[88:91]
	v_mfma_f32_16x16x32_bf16 v[76:79], v[128:131], v[220:223], v[76:79]
	v_mfma_f32_16x16x32_bf16 v[72:75], v[146:149], v[220:223], v[72:75]
	v_mfma_f32_16x16x32_bf16 v[124:127], v[132:135], v[178:181], v[124:127]
	v_mfma_f32_16x16x32_bf16 v[120:123], v[150:153], v[178:181], v[120:123]
	v_mfma_f32_16x16x32_bf16 v[108:111], v[132:135], v[194:197], v[108:111]
	v_mfma_f32_16x16x32_bf16 v[104:107], v[150:153], v[194:197], v[104:107]
	v_mfma_f32_16x16x32_bf16 v[92:95], v[132:135], v[216:219], v[92:95]
	v_mfma_f32_16x16x32_bf16 v[88:91], v[150:153], v[216:219], v[88:91]
	v_mfma_f32_16x16x32_bf16 v[76:79], v[132:135], v[224:227], v[76:79]
	v_mfma_f32_16x16x32_bf16 v[72:75], v[150:153], v[224:227], v[72:75]
	s_setprio 0
	s_setprio 1
	v_mfma_f32_16x16x32_bf16 v[116:119], v[158:161], v[174:177], v[116:119]
	v_mfma_f32_16x16x32_bf16 v[112:115], v[166:169], v[174:177], v[112:115]
	v_mfma_f32_16x16x32_bf16 v[100:103], v[158:161], v[182:185], v[100:103]
	v_mfma_f32_16x16x32_bf16 v[96:99], v[166:169], v[182:185], v[96:99]
	v_mfma_f32_16x16x32_bf16 v[84:87], v[158:161], v[202:205], v[84:87]
	v_mfma_f32_16x16x32_bf16 v[80:83], v[166:169], v[202:205], v[80:83]
	v_mfma_f32_16x16x32_bf16 v[68:71], v[158:161], v[220:223], v[68:71]
	v_mfma_f32_16x16x32_bf16 v[64:67], v[166:169], v[220:223], v[64:67]
	v_mfma_f32_16x16x32_bf16 v[116:119], v[162:165], v[178:181], v[116:119]
	v_mfma_f32_16x16x32_bf16 v[112:115], v[170:173], v[178:181], v[112:115]
	v_mfma_f32_16x16x32_bf16 v[100:103], v[162:165], v[194:197], v[100:103]
	v_mfma_f32_16x16x32_bf16 v[96:99], v[170:173], v[194:197], v[96:99]
	v_mfma_f32_16x16x32_bf16 v[84:87], v[162:165], v[216:219], v[84:87]
	v_mfma_f32_16x16x32_bf16 v[80:83], v[170:173], v[216:219], v[80:83]
	v_mfma_f32_16x16x32_bf16 v[68:71], v[162:165], v[224:227], v[68:71]
	v_mfma_f32_16x16x32_bf16 v[64:67], v[170:173], v[224:227], v[64:67]
	s_setprio 0
	s_barrier
	s_add_i32 s37, vcc_lo, s60
	v_lshl_add_u64 v[186:187], s[42:43], 0, v[188:189]
	s_mov_b32 m0, s37
	ds_read_b128 v[174:177], v157 offset:16384
	ds_read_b128 v[178:181], v157 offset:17408
	ds_read_b128 v[182:185], v157 offset:18432
	ds_read_b128 v[194:197], v157 offset:19456
	ds_read_b128 v[202:205], v157 offset:20480
	ds_read_b128 v[216:219], v157 offset:21504
	ds_read_b128 v[220:223], v157 offset:22528
	ds_read_b128 v[224:227], v157 offset:23552
	global_load_lds_dwordx4 v[186:187], off
	s_add_i32 m0, s37, 0x2000
	s_add_u32 vcc_lo, s42, 0x40000
	v_lshl_add_u64 v[228:229], s[42:43], 0, v[136:137]
	s_addc_u32 vcc_hi, s43, 0
	s_add_i32 s36, s36, s60
	global_load_lds_dwordx4 v[228:229], off
	v_lshl_add_u64 v[230:231], vcc, 0, v[188:189]
	s_mov_b32 m0, s36
	v_lshl_add_u64 v[232:233], s[56:57], 0, v[138:139]
	global_load_lds_dwordx4 v[230:231], off
	v_lshl_add_u64 v[230:231], vcc, 0, v[136:137]
	s_add_i32 m0, s36, 0x2000
	s_nop 0
	global_load_lds_dwordx4 v[230:231], off
	v_lshl_add_u64 v[230:231], s[56:57], 0, v[140:141]
	s_mov_b32 m0, s5
	s_nop 0
	global_load_lds_dwordx4 v[230:231], off
	s_mov_b32 m0, s6
	s_nop 0
	global_load_lds_dwordx4 v[232:233], off
	s_waitcnt vmcnt(8)
	s_waitcnt lgkmcnt(0)
	s_barrier
	s_setprio 1
	s_waitcnt lgkmcnt(0)
	v_mfma_f32_16x16x32_bf16 v[60:63], v[128:131], v[174:177], v[60:63]
	v_mfma_f32_16x16x32_bf16 v[56:59], v[146:149], v[174:177], v[56:59]
	v_mfma_f32_16x16x32_bf16 v[44:47], v[128:131], v[182:185], v[44:47]
	v_mfma_f32_16x16x32_bf16 v[40:43], v[146:149], v[182:185], v[40:43]
	v_mfma_f32_16x16x32_bf16 v[28:31], v[128:131], v[202:205], v[28:31]
	v_mfma_f32_16x16x32_bf16 v[24:27], v[146:149], v[202:205], v[24:27]
	v_mfma_f32_16x16x32_bf16 v[12:15], v[128:131], v[220:223], v[12:15]
	v_mfma_f32_16x16x32_bf16 v[8:11], v[146:149], v[220:223], v[8:11]
	v_mfma_f32_16x16x32_bf16 v[60:63], v[132:135], v[178:181], v[60:63]
	v_mfma_f32_16x16x32_bf16 v[56:59], v[150:153], v[178:181], v[56:59]
	v_mfma_f32_16x16x32_bf16 v[44:47], v[132:135], v[194:197], v[44:47]
	v_mfma_f32_16x16x32_bf16 v[40:43], v[150:153], v[194:197], v[40:43]
	v_mfma_f32_16x16x32_bf16 v[28:31], v[132:135], v[216:219], v[28:31]
	v_mfma_f32_16x16x32_bf16 v[24:27], v[150:153], v[216:219], v[24:27]
	v_mfma_f32_16x16x32_bf16 v[12:15], v[132:135], v[224:227], v[12:15]
	v_mfma_f32_16x16x32_bf16 v[8:11], v[150:153], v[224:227], v[8:11]
	s_setprio 0
	s_setprio 1
	v_mfma_f32_16x16x32_bf16 v[52:55], v[158:161], v[174:177], v[52:55]
	v_mfma_f32_16x16x32_bf16 v[48:51], v[166:169], v[174:177], v[48:51]
	v_mfma_f32_16x16x32_bf16 v[36:39], v[158:161], v[182:185], v[36:39]
	v_mfma_f32_16x16x32_bf16 v[32:35], v[166:169], v[182:185], v[32:35]
	v_mfma_f32_16x16x32_bf16 v[20:23], v[158:161], v[202:205], v[20:23]
	v_mfma_f32_16x16x32_bf16 v[16:19], v[166:169], v[202:205], v[16:19]
	v_mfma_f32_16x16x32_bf16 v[4:7], v[158:161], v[220:223], v[4:7]
	v_mfma_f32_16x16x32_bf16 v[0:3], v[166:169], v[220:223], v[0:3]
	v_mfma_f32_16x16x32_bf16 v[52:55], v[162:165], v[178:181], v[52:55]
	v_mfma_f32_16x16x32_bf16 v[48:51], v[170:173], v[178:181], v[48:51]
	v_mfma_f32_16x16x32_bf16 v[36:39], v[162:165], v[194:197], v[36:39]
	v_mfma_f32_16x16x32_bf16 v[32:35], v[170:173], v[194:197], v[32:35]
	v_mfma_f32_16x16x32_bf16 v[20:23], v[162:165], v[216:219], v[20:23]
	v_mfma_f32_16x16x32_bf16 v[16:19], v[170:173], v[216:219], v[16:19]
	v_mfma_f32_16x16x32_bf16 v[4:7], v[162:165], v[224:227], v[4:7]
	v_mfma_f32_16x16x32_bf16 v[0:3], v[170:173], v[224:227], v[0:3]
	s_setprio 0
	s_barrier
	s_add_i32 s36, 0, 0x18000
	s_add_i32 s37, 0, 0x1c000
	s_add_u32 s56, s56, 0x40000
	s_addc_u32 s57, s57, 0
	s_mov_b32 m0, s7
	v_lshl_add_u64 v[244:245], s[56:57], 0, v[140:141]
	global_load_lds_dwordx4 v[244:245], off
	v_lshl_add_u64 v[246:247], s[56:57], 0, v[138:139]
	s_mov_b32 m0, s8
	s_nop 0
	global_load_lds_dwordx4 v[246:247], off
	v_add_u32_e32 v150, s36, v156
	v_add_u32_e32 v170, s37, v156
	ds_read_b128 v[128:131], v150
	ds_read_b128 v[132:135], v150 offset:1024
	ds_read_b128 v[146:149], v150 offset:2048
	ds_read_b128 v[150:153], v150 offset:3072
	ds_read_b128 v[158:161], v170
	ds_read_b128 v[162:165], v170 offset:1024
	ds_read_b128 v[166:169], v170 offset:2048
	ds_read_b128 v[170:173], v170 offset:3072
	ds_read_b128 v[174:177], v157 offset:32768
	ds_read_b128 v[178:181], v157 offset:33792
	ds_read_b128 v[182:185], v157 offset:34816
	ds_read_b128 v[194:197], v157 offset:35840
	ds_read_b128 v[202:205], v157 offset:36864
	ds_read_b128 v[216:219], v157 offset:37888
	ds_read_b128 v[220:223], v157 offset:38912
	ds_read_b128 v[224:227], v157 offset:39936
	s_waitcnt vmcnt(8)
	s_waitcnt lgkmcnt(0)


	s_barrier
	s_setprio 1
	s_waitcnt lgkmcnt(0)
	v_mfma_f32_16x16x32_bf16 v[124:127], v[128:131], v[174:177], v[124:127]
	v_mfma_f32_16x16x32_bf16 v[120:123], v[146:149], v[174:177], v[120:123]
	v_mfma_f32_16x16x32_bf16 v[108:111], v[128:131], v[182:185], v[108:111]
	v_mfma_f32_16x16x32_bf16 v[104:107], v[146:149], v[182:185], v[104:107]
	v_mfma_f32_16x16x32_bf16 v[92:95], v[128:131], v[202:205], v[92:95]
	v_mfma_f32_16x16x32_bf16 v[88:91], v[146:149], v[202:205], v[88:91]
	v_mfma_f32_16x16x32_bf16 v[76:79], v[128:131], v[220:223], v[76:79]
	v_mfma_f32_16x16x32_bf16 v[72:75], v[146:149], v[220:223], v[72:75]
	v_mfma_f32_16x16x32_bf16 v[124:127], v[132:135], v[178:181], v[124:127]
	v_mfma_f32_16x16x32_bf16 v[120:123], v[150:153], v[178:181], v[120:123]
	v_mfma_f32_16x16x32_bf16 v[108:111], v[132:135], v[194:197], v[108:111]
	v_mfma_f32_16x16x32_bf16 v[104:107], v[150:153], v[194:197], v[104:107]
	v_mfma_f32_16x16x32_bf16 v[92:95], v[132:135], v[216:219], v[92:95]
	v_mfma_f32_16x16x32_bf16 v[88:91], v[150:153], v[216:219], v[88:91]
	v_mfma_f32_16x16x32_bf16 v[76:79], v[132:135], v[224:227], v[76:79]
	v_mfma_f32_16x16x32_bf16 v[72:75], v[150:153], v[224:227], v[72:75]
	s_setprio 0
	s_setprio 1
	v_mfma_f32_16x16x32_bf16 v[116:119], v[158:161], v[174:177], v[116:119]
	v_mfma_f32_16x16x32_bf16 v[112:115], v[166:169], v[174:177], v[112:115]
	v_mfma_f32_16x16x32_bf16 v[100:103], v[158:161], v[182:185], v[100:103]
	v_mfma_f32_16x16x32_bf16 v[96:99], v[166:169], v[182:185], v[96:99]
	v_mfma_f32_16x16x32_bf16 v[84:87], v[158:161], v[202:205], v[84:87]
	v_mfma_f32_16x16x32_bf16 v[80:83], v[166:169], v[202:205], v[80:83]
	v_mfma_f32_16x16x32_bf16 v[68:71], v[158:161], v[220:223], v[68:71]
	v_mfma_f32_16x16x32_bf16 v[64:67], v[166:169], v[220:223], v[64:67]
	v_mfma_f32_16x16x32_bf16 v[116:119], v[162:165], v[178:181], v[116:119]
	v_mfma_f32_16x16x32_bf16 v[112:115], v[170:173], v[178:181], v[112:115]
	v_mfma_f32_16x16x32_bf16 v[100:103], v[162:165], v[194:197], v[100:103]
	v_mfma_f32_16x16x32_bf16 v[96:99], v[170:173], v[194:197], v[96:99]
	v_mfma_f32_16x16x32_bf16 v[84:87], v[162:165], v[216:219], v[84:87]
	v_mfma_f32_16x16x32_bf16 v[80:83], v[170:173], v[216:219], v[80:83]
	v_mfma_f32_16x16x32_bf16 v[68:71], v[162:165], v[224:227], v[68:71]
	v_mfma_f32_16x16x32_bf16 v[64:67], v[170:173], v[224:227], v[64:67]
	s_setprio 0
	s_barrier
	s_add_i32 s36, s36, s60
	v_lshl_add_u64 v[186:187], v[186:187], 0, s[62:63]
	s_mov_b32 m0, s36
	ds_read_b128 v[174:177], v157 offset:49152
	ds_read_b128 v[178:181], v157 offset:50176
	ds_read_b128 v[182:185], v157 offset:51200
	ds_read_b128 v[194:197], v157 offset:52224
	ds_read_b128 v[202:205], v157 offset:53248
	ds_read_b128 v[216:219], v157 offset:54272
	ds_read_b128 v[220:223], v157 offset:55296
	ds_read_b128 v[224:227], v157 offset:56320
	global_load_lds_dwordx4 v[186:187], off
	s_add_i32 m0, s36, 0x2000
	s_add_u32 s42, s42, 0x40080
	v_lshl_add_u64 v[186:187], v[228:229], 0, s[62:63]
	s_addc_u32 s43, s43, 0
	s_add_i32 s36, s37, s60
	global_load_lds_dwordx4 v[186:187], off
	v_lshl_add_u64 v[186:187], s[42:43], 0, v[188:189]
	s_mov_b32 m0, s36
	s_nop 0
	global_load_lds_dwordx4 v[186:187], off
	v_lshl_add_u64 v[186:187], s[42:43], 0, v[136:137]
	s_add_i32 m0, s36, 0x2000
	s_nop 0
	global_load_lds_dwordx4 v[186:187], off
	v_lshl_add_u64 v[186:187], v[230:231], 0, s[62:63]
	s_mov_b32 m0, s85
	s_nop 0
	global_load_lds_dwordx4 v[186:187], off
	v_lshl_add_u64 v[186:187], v[232:233], 0, s[62:63]
	s_mov_b32 m0, s86
	s_nop 0
	global_load_lds_dwordx4 v[186:187], off
	s_waitcnt vmcnt(8)
	s_waitcnt lgkmcnt(0)
	s_barrier
	s_setprio 1
	s_waitcnt lgkmcnt(0)
	v_mfma_f32_16x16x32_bf16 v[60:63], v[128:131], v[174:177], v[60:63]
	v_mfma_f32_16x16x32_bf16 v[56:59], v[146:149], v[174:177], v[56:59]
	v_mfma_f32_16x16x32_bf16 v[44:47], v[128:131], v[182:185], v[44:47]
	v_mfma_f32_16x16x32_bf16 v[40:43], v[146:149], v[182:185], v[40:43]
	v_mfma_f32_16x16x32_bf16 v[28:31], v[128:131], v[202:205], v[28:31]
	v_mfma_f32_16x16x32_bf16 v[24:27], v[146:149], v[202:205], v[24:27]
	v_mfma_f32_16x16x32_bf16 v[12:15], v[128:131], v[220:223], v[12:15]
	v_mfma_f32_16x16x32_bf16 v[8:11], v[146:149], v[220:223], v[8:11]
	v_mfma_f32_16x16x32_bf16 v[60:63], v[132:135], v[178:181], v[60:63]
	v_mfma_f32_16x16x32_bf16 v[56:59], v[150:153], v[178:181], v[56:59]
	v_mfma_f32_16x16x32_bf16 v[44:47], v[132:135], v[194:197], v[44:47]
	v_mfma_f32_16x16x32_bf16 v[40:43], v[150:153], v[194:197], v[40:43]
	v_mfma_f32_16x16x32_bf16 v[28:31], v[132:135], v[216:219], v[28:31]
	v_mfma_f32_16x16x32_bf16 v[24:27], v[150:153], v[216:219], v[24:27]
	v_mfma_f32_16x16x32_bf16 v[12:15], v[132:135], v[224:227], v[12:15]
	v_mfma_f32_16x16x32_bf16 v[8:11], v[150:153], v[224:227], v[8:11]
	s_setprio 0
	s_setprio 1
	v_mfma_f32_16x16x32_bf16 v[52:55], v[158:161], v[174:177], v[52:55]
	v_mfma_f32_16x16x32_bf16 v[48:51], v[166:169], v[174:177], v[48:51]
	v_mfma_f32_16x16x32_bf16 v[36:39], v[158:161], v[182:185], v[36:39]
	v_mfma_f32_16x16x32_bf16 v[32:35], v[166:169], v[182:185], v[32:35]
	v_mfma_f32_16x16x32_bf16 v[20:23], v[158:161], v[202:205], v[20:23]
	v_mfma_f32_16x16x32_bf16 v[16:19], v[166:169], v[202:205], v[16:19]
	v_mfma_f32_16x16x32_bf16 v[4:7], v[158:161], v[220:223], v[4:7]
	v_mfma_f32_16x16x32_bf16 v[0:3], v[166:169], v[220:223], v[0:3]
	v_mfma_f32_16x16x32_bf16 v[52:55], v[162:165], v[178:181], v[52:55]
	v_mfma_f32_16x16x32_bf16 v[48:51], v[170:173], v[178:181], v[48:51]
	v_mfma_f32_16x16x32_bf16 v[36:39], v[162:165], v[194:197], v[36:39]
	v_mfma_f32_16x16x32_bf16 v[32:35], v[170:173], v[194:197], v[32:35]
	v_mfma_f32_16x16x32_bf16 v[20:23], v[162:165], v[216:219], v[20:23]
	v_mfma_f32_16x16x32_bf16 v[16:19], v[170:173], v[216:219], v[16:19]
	v_mfma_f32_16x16x32_bf16 v[4:7], v[162:165], v[224:227], v[4:7]
	v_mfma_f32_16x16x32_bf16 v[0:3], v[170:173], v[224:227], v[0:3]
	s_setprio 0
	s_barrier
	s_add_u32 s40, s40, 0x100
	s_addc_u32 s41, s41, 0
	s_add_u32 s89, s89, 0x100
	s_addc_u32 s94, s94, 0
	s_cmp_ge_i32 s95, s81
	s_mov_b32 s42, s95
	s_cbranch_scc0 .LBB0_578

.LBB0_734:
	s_add_i32 s85, s48, 2
	s_add_u32 s49, s38, 0xfffc0080
	s_addc_u32 s50, s39, -1
	s_add_i32 s86, 0, 0x10000
	s_cmp_eq_u32 s70, s48
	s_cselect_b32 s51, s41, s50
	s_cselect_b32 s50, s43, s49
	v_add_u32_e32 v146, s86, v150
	s_cselect_b32 s49, s81, s84
	s_cselect_b32 s48, s82, s83
	v_lshl_add_u64 v[244:245], s[38:39], 0, v[134:135]
	s_add_i32 m0, s55, 0xc000
	s_nop 0
	global_load_lds_dwordx4 v[244:245], off
	v_lshl_add_u64 v[246:247], s[38:39], 0, v[136:137]
	s_add_i32 m0, s55, 0xe000
	s_nop 0
	global_load_lds_dwordx4 v[246:247], off
	s_add_i32 s88, 0, 0x14000
	ds_read_b128 v[138:141], v146
	ds_read_b128 v[142:145], v146 offset:1024
	ds_read_b128 v[152:155], v146 offset:2048
	ds_read_b128 v[156:159], v146 offset:3072
	v_add_u32_e32 v146, s88, v150
	ds_read_b128 v[160:163], v146
	ds_read_b128 v[164:167], v146 offset:1024
	ds_read_b128 v[168:171], v146 offset:2048
	ds_read_b128 v[172:175], v146 offset:3072
	ds_read_b128 v[176:179], v151
	ds_read_b128 v[180:183], v151 offset:1024
	ds_read_b128 v[184:187], v151 offset:2048
	ds_read_b128 v[194:197], v151 offset:3072
	ds_read_b128 v[202:205], v151 offset:4096
	ds_read_b128 v[216:219], v151 offset:5120
	ds_read_b128 v[220:223], v151 offset:6144
	ds_read_b128 v[224:227], v151 offset:7168
	s_waitcnt vmcnt(8)
	s_waitcnt lgkmcnt(0)


	s_barrier
	s_setprio 1
	s_waitcnt lgkmcnt(0)
	v_mfma_f32_16x16x32_bf16 v[124:127], v[138:141], v[176:179], v[124:127]
	v_mfma_f32_16x16x32_bf16 v[120:123], v[152:155], v[176:179], v[120:123]
	v_mfma_f32_16x16x32_bf16 v[108:111], v[138:141], v[184:187], v[108:111]
	v_mfma_f32_16x16x32_bf16 v[104:107], v[152:155], v[184:187], v[104:107]
	v_mfma_f32_16x16x32_bf16 v[92:95], v[138:141], v[202:205], v[92:95]
	v_mfma_f32_16x16x32_bf16 v[88:91], v[152:155], v[202:205], v[88:91]
	v_mfma_f32_16x16x32_bf16 v[76:79], v[138:141], v[220:223], v[76:79]
	v_mfma_f32_16x16x32_bf16 v[72:75], v[152:155], v[220:223], v[72:75]
	v_mfma_f32_16x16x32_bf16 v[124:127], v[142:145], v[180:183], v[124:127]
	v_mfma_f32_16x16x32_bf16 v[120:123], v[156:159], v[180:183], v[120:123]
	v_mfma_f32_16x16x32_bf16 v[108:111], v[142:145], v[194:197], v[108:111]
	v_mfma_f32_16x16x32_bf16 v[104:107], v[156:159], v[194:197], v[104:107]
	v_mfma_f32_16x16x32_bf16 v[92:95], v[142:145], v[216:219], v[92:95]
	v_mfma_f32_16x16x32_bf16 v[88:91], v[156:159], v[216:219], v[88:91]
	v_mfma_f32_16x16x32_bf16 v[76:79], v[142:145], v[224:227], v[76:79]
	v_mfma_f32_16x16x32_bf16 v[72:75], v[156:159], v[224:227], v[72:75]
	s_setprio 0
	s_setprio 1
	v_mfma_f32_16x16x32_bf16 v[116:119], v[160:163], v[176:179], v[116:119]
	v_mfma_f32_16x16x32_bf16 v[112:115], v[168:171], v[176:179], v[112:115]
	v_mfma_f32_16x16x32_bf16 v[100:103], v[160:163], v[184:187], v[100:103]
	v_mfma_f32_16x16x32_bf16 v[96:99], v[168:171], v[184:187], v[96:99]
	v_mfma_f32_16x16x32_bf16 v[84:87], v[160:163], v[202:205], v[84:87]
	v_mfma_f32_16x16x32_bf16 v[80:83], v[168:171], v[202:205], v[80:83]
	v_mfma_f32_16x16x32_bf16 v[68:71], v[160:163], v[220:223], v[68:71]
	v_mfma_f32_16x16x32_bf16 v[64:67], v[168:171], v[220:223], v[64:67]
	v_mfma_f32_16x16x32_bf16 v[116:119], v[164:167], v[180:183], v[116:119]
	v_mfma_f32_16x16x32_bf16 v[112:115], v[172:175], v[180:183], v[112:115]
	v_mfma_f32_16x16x32_bf16 v[100:103], v[164:167], v[194:197], v[100:103]
	v_mfma_f32_16x16x32_bf16 v[96:99], v[172:175], v[194:197], v[96:99]
	v_mfma_f32_16x16x32_bf16 v[84:87], v[164:167], v[216:219], v[84:87]
	v_mfma_f32_16x16x32_bf16 v[80:83], v[172:175], v[216:219], v[80:83]
	v_mfma_f32_16x16x32_bf16 v[68:71], v[164:167], v[224:227], v[68:71]
	v_mfma_f32_16x16x32_bf16 v[64:67], v[172:175], v[224:227], v[64:67]
	s_setprio 0
	s_barrier
	s_add_i32 s86, s86, s54
	v_lshl_add_u64 v[146:147], s[48:49], 0, v[188:189]
	s_mov_b32 m0, s86
	ds_read_b128 v[176:179], v151 offset:16384
	ds_read_b128 v[180:183], v151 offset:17408
	ds_read_b128 v[184:187], v151 offset:18432
	ds_read_b128 v[194:197], v151 offset:19456
	ds_read_b128 v[202:205], v151 offset:20480
	ds_read_b128 v[216:219], v151 offset:21504
	ds_read_b128 v[220:223], v151 offset:22528
	ds_read_b128 v[224:227], v151 offset:23552
	global_load_lds_dwordx4 v[146:147], off
	s_add_i32 m0, s86, 0x2000
	s_add_u32 s86, s48, 0x40000
	v_lshl_add_u64 v[228:229], s[48:49], 0, v[128:129]
	s_addc_u32 s87, s49, 0
	s_add_i32 s88, s88, s54
	global_load_lds_dwordx4 v[228:229], off
	v_lshl_add_u64 v[230:231], s[86:87], 0, v[188:189]
	s_mov_b32 m0, s88
	v_lshl_add_u64 v[232:233], s[50:51], 0, v[130:131]
	global_load_lds_dwordx4 v[230:231], off
	v_lshl_add_u64 v[230:231], s[86:87], 0, v[128:129]
	s_add_i32 m0, s88, 0x2000
	s_nop 0
	global_load_lds_dwordx4 v[230:231], off
	v_lshl_add_u64 v[230:231], s[50:51], 0, v[132:133]
	s_mov_b32 m0, s55
	s_nop 0
	global_load_lds_dwordx4 v[230:231], off
	s_mov_b32 m0, s56
	s_nop 0
	global_load_lds_dwordx4 v[232:233], off
	s_waitcnt vmcnt(8)
	s_waitcnt lgkmcnt(0)
	s_barrier
	s_setprio 1
	s_waitcnt lgkmcnt(0)
	v_mfma_f32_16x16x32_bf16 v[60:63], v[138:141], v[176:179], v[60:63]
	v_mfma_f32_16x16x32_bf16 v[56:59], v[152:155], v[176:179], v[56:59]
	v_mfma_f32_16x16x32_bf16 v[44:47], v[138:141], v[184:187], v[44:47]
	v_mfma_f32_16x16x32_bf16 v[40:43], v[152:155], v[184:187], v[40:43]
	v_mfma_f32_16x16x32_bf16 v[28:31], v[138:141], v[202:205], v[28:31]
	v_mfma_f32_16x16x32_bf16 v[24:27], v[152:155], v[202:205], v[24:27]
	v_mfma_f32_16x16x32_bf16 v[12:15], v[138:141], v[220:223], v[12:15]
	v_mfma_f32_16x16x32_bf16 v[8:11], v[152:155], v[220:223], v[8:11]
	v_mfma_f32_16x16x32_bf16 v[60:63], v[142:145], v[180:183], v[60:63]
	v_mfma_f32_16x16x32_bf16 v[56:59], v[156:159], v[180:183], v[56:59]
	v_mfma_f32_16x16x32_bf16 v[44:47], v[142:145], v[194:197], v[44:47]
	v_mfma_f32_16x16x32_bf16 v[40:43], v[156:159], v[194:197], v[40:43]
	v_mfma_f32_16x16x32_bf16 v[28:31], v[142:145], v[216:219], v[28:31]
	v_mfma_f32_16x16x32_bf16 v[24:27], v[156:159], v[216:219], v[24:27]
	v_mfma_f32_16x16x32_bf16 v[12:15], v[142:145], v[224:227], v[12:15]
	v_mfma_f32_16x16x32_bf16 v[8:11], v[156:159], v[224:227], v[8:11]
	s_setprio 0
	s_setprio 1
	v_mfma_f32_16x16x32_bf16 v[52:55], v[160:163], v[176:179], v[52:55]
	v_mfma_f32_16x16x32_bf16 v[48:51], v[168:171], v[176:179], v[48:51]
	v_mfma_f32_16x16x32_bf16 v[36:39], v[160:163], v[184:187], v[36:39]
	v_mfma_f32_16x16x32_bf16 v[32:35], v[168:171], v[184:187], v[32:35]
	v_mfma_f32_16x16x32_bf16 v[20:23], v[160:163], v[202:205], v[20:23]
	v_mfma_f32_16x16x32_bf16 v[16:19], v[168:171], v[202:205], v[16:19]
	v_mfma_f32_16x16x32_bf16 v[4:7], v[160:163], v[220:223], v[4:7]
	v_mfma_f32_16x16x32_bf16 v[0:3], v[168:171], v[220:223], v[0:3]
	v_mfma_f32_16x16x32_bf16 v[52:55], v[164:167], v[180:183], v[52:55]
	v_mfma_f32_16x16x32_bf16 v[48:51], v[172:175], v[180:183], v[48:51]
	v_mfma_f32_16x16x32_bf16 v[36:39], v[164:167], v[194:197], v[36:39]
	v_mfma_f32_16x16x32_bf16 v[32:35], v[172:175], v[194:197], v[32:35]
	v_mfma_f32_16x16x32_bf16 v[20:23], v[164:167], v[216:219], v[20:23]
	v_mfma_f32_16x16x32_bf16 v[16:19], v[172:175], v[216:219], v[16:19]
	v_mfma_f32_16x16x32_bf16 v[4:7], v[164:167], v[224:227], v[4:7]
	v_mfma_f32_16x16x32_bf16 v[0:3], v[172:175], v[224:227], v[0:3]
	s_setprio 0
	s_barrier
	s_add_i32 s86, 0, 0x18000
	s_add_i32 s87, 0, 0x1c000
	s_add_u32 s50, s50, 0x40000
	s_addc_u32 s51, s51, 0
	s_mov_b32 m0, s57
	v_lshl_add_u64 v[244:245], s[50:51], 0, v[132:133]
	global_load_lds_dwordx4 v[244:245], off
	v_lshl_add_u64 v[246:247], s[50:51], 0, v[130:131]
	s_mov_b32 m0, s58
	s_nop 0
	global_load_lds_dwordx4 v[246:247], off
	v_add_u32_e32 v156, s86, v150
	v_add_u32_e32 v172, s87, v150
	ds_read_b128 v[138:141], v156
	ds_read_b128 v[142:145], v156 offset:1024
	ds_read_b128 v[152:155], v156 offset:2048
	ds_read_b128 v[156:159], v156 offset:3072
	ds_read_b128 v[160:163], v172
	ds_read_b128 v[164:167], v172 offset:1024
	ds_read_b128 v[168:171], v172 offset:2048
	ds_read_b128 v[172:175], v172 offset:3072
	ds_read_b128 v[176:179], v151 offset:32768
	ds_read_b128 v[180:183], v151 offset:33792
	ds_read_b128 v[184:187], v151 offset:34816
	ds_read_b128 v[194:197], v151 offset:35840
	ds_read_b128 v[202:205], v151 offset:36864
	ds_read_b128 v[216:219], v151 offset:37888
	ds_read_b128 v[220:223], v151 offset:38912
	ds_read_b128 v[224:227], v151 offset:39936
	s_waitcnt vmcnt(8)
	s_waitcnt lgkmcnt(0)


	s_barrier
	s_setprio 1
	s_waitcnt lgkmcnt(0)
	v_mfma_f32_16x16x32_bf16 v[124:127], v[138:141], v[176:179], v[124:127]
	v_mfma_f32_16x16x32_bf16 v[120:123], v[152:155], v[176:179], v[120:123]
	v_mfma_f32_16x16x32_bf16 v[108:111], v[138:141], v[184:187], v[108:111]
	v_mfma_f32_16x16x32_bf16 v[104:107], v[152:155], v[184:187], v[104:107]
	v_mfma_f32_16x16x32_bf16 v[92:95], v[138:141], v[202:205], v[92:95]
	v_mfma_f32_16x16x32_bf16 v[88:91], v[152:155], v[202:205], v[88:91]
	v_mfma_f32_16x16x32_bf16 v[76:79], v[138:141], v[220:223], v[76:79]
	v_mfma_f32_16x16x32_bf16 v[72:75], v[152:155], v[220:223], v[72:75]
	v_mfma_f32_16x16x32_bf16 v[124:127], v[142:145], v[180:183], v[124:127]
	v_mfma_f32_16x16x32_bf16 v[120:123], v[156:159], v[180:183], v[120:123]
	v_mfma_f32_16x16x32_bf16 v[108:111], v[142:145], v[194:197], v[108:111]
	v_mfma_f32_16x16x32_bf16 v[104:107], v[156:159], v[194:197], v[104:107]
	v_mfma_f32_16x16x32_bf16 v[92:95], v[142:145], v[216:219], v[92:95]
	v_mfma_f32_16x16x32_bf16 v[88:91], v[156:159], v[216:219], v[88:91]
	v_mfma_f32_16x16x32_bf16 v[76:79], v[142:145], v[224:227], v[76:79]
	v_mfma_f32_16x16x32_bf16 v[72:75], v[156:159], v[224:227], v[72:75]
	s_setprio 0
	s_setprio 1
	v_mfma_f32_16x16x32_bf16 v[116:119], v[160:163], v[176:179], v[116:119]
	v_mfma_f32_16x16x32_bf16 v[112:115], v[168:171], v[176:179], v[112:115]
	v_mfma_f32_16x16x32_bf16 v[100:103], v[160:163], v[184:187], v[100:103]
	v_mfma_f32_16x16x32_bf16 v[96:99], v[168:171], v[184:187], v[96:99]
	v_mfma_f32_16x16x32_bf16 v[84:87], v[160:163], v[202:205], v[84:87]
	v_mfma_f32_16x16x32_bf16 v[80:83], v[168:171], v[202:205], v[80:83]
	v_mfma_f32_16x16x32_bf16 v[68:71], v[160:163], v[220:223], v[68:71]
	v_mfma_f32_16x16x32_bf16 v[64:67], v[168:171], v[220:223], v[64:67]
	v_mfma_f32_16x16x32_bf16 v[116:119], v[164:167], v[180:183], v[116:119]
	v_mfma_f32_16x16x32_bf16 v[112:115], v[172:175], v[180:183], v[112:115]
	v_mfma_f32_16x16x32_bf16 v[100:103], v[164:167], v[194:197], v[100:103]
	v_mfma_f32_16x16x32_bf16 v[96:99], v[172:175], v[194:197], v[96:99]
	v_mfma_f32_16x16x32_bf16 v[84:87], v[164:167], v[216:219], v[84:87]
	v_mfma_f32_16x16x32_bf16 v[80:83], v[172:175], v[216:219], v[80:83]
	v_mfma_f32_16x16x32_bf16 v[68:71], v[164:167], v[224:227], v[68:71]
	v_mfma_f32_16x16x32_bf16 v[64:67], v[172:175], v[224:227], v[64:67]
	s_setprio 0
	s_barrier
	s_add_i32 s50, s86, s54
	v_lshl_add_u64 v[146:147], v[146:147], 0, s[62:63]
	s_mov_b32 m0, s50
	ds_read_b128 v[176:179], v151 offset:49152
	ds_read_b128 v[180:183], v151 offset:50176
	ds_read_b128 v[184:187], v151 offset:51200
	ds_read_b128 v[194:197], v151 offset:52224
	ds_read_b128 v[202:205], v151 offset:53248
	ds_read_b128 v[216:219], v151 offset:54272
	ds_read_b128 v[220:223], v151 offset:55296
	ds_read_b128 v[224:227], v151 offset:56320
	global_load_lds_dwordx4 v[146:147], off
	s_add_i32 m0, s50, 0x2000
	s_add_u32 s48, s48, 0x40080
	v_lshl_add_u64 v[146:147], v[228:229], 0, s[62:63]
	s_addc_u32 s49, s49, 0
	s_add_i32 s50, s87, s54
	global_load_lds_dwordx4 v[146:147], off
	v_lshl_add_u64 v[146:147], s[48:49], 0, v[188:189]
	s_mov_b32 m0, s50
	s_nop 0
	global_load_lds_dwordx4 v[146:147], off
	v_lshl_add_u64 v[146:147], s[48:49], 0, v[128:129]
	s_add_i32 m0, s50, 0x2000
	s_nop 0
	global_load_lds_dwordx4 v[146:147], off
	v_lshl_add_u64 v[146:147], v[230:231], 0, s[62:63]
	s_mov_b32 m0, s67
	s_nop 0
	global_load_lds_dwordx4 v[146:147], off
	v_lshl_add_u64 v[146:147], v[232:233], 0, s[62:63]
	s_mov_b32 m0, s69
	s_nop 0
	global_load_lds_dwordx4 v[146:147], off
	s_waitcnt vmcnt(8)
	s_waitcnt lgkmcnt(0)
	s_barrier
	s_setprio 1
	s_waitcnt lgkmcnt(0)
	v_mfma_f32_16x16x32_bf16 v[60:63], v[138:141], v[176:179], v[60:63]
	v_mfma_f32_16x16x32_bf16 v[56:59], v[152:155], v[176:179], v[56:59]
	v_mfma_f32_16x16x32_bf16 v[44:47], v[138:141], v[184:187], v[44:47]
	v_mfma_f32_16x16x32_bf16 v[40:43], v[152:155], v[184:187], v[40:43]
	v_mfma_f32_16x16x32_bf16 v[28:31], v[138:141], v[202:205], v[28:31]
	v_mfma_f32_16x16x32_bf16 v[24:27], v[152:155], v[202:205], v[24:27]
	v_mfma_f32_16x16x32_bf16 v[12:15], v[138:141], v[220:223], v[12:15]
	v_mfma_f32_16x16x32_bf16 v[8:11], v[152:155], v[220:223], v[8:11]
	v_mfma_f32_16x16x32_bf16 v[60:63], v[142:145], v[180:183], v[60:63]
	v_mfma_f32_16x16x32_bf16 v[56:59], v[156:159], v[180:183], v[56:59]
	v_mfma_f32_16x16x32_bf16 v[44:47], v[142:145], v[194:197], v[44:47]
	v_mfma_f32_16x16x32_bf16 v[40:43], v[156:159], v[194:197], v[40:43]
	v_mfma_f32_16x16x32_bf16 v[28:31], v[142:145], v[216:219], v[28:31]
	v_mfma_f32_16x16x32_bf16 v[24:27], v[156:159], v[216:219], v[24:27]
	v_mfma_f32_16x16x32_bf16 v[12:15], v[142:145], v[224:227], v[12:15]
	v_mfma_f32_16x16x32_bf16 v[8:11], v[156:159], v[224:227], v[8:11]
	s_setprio 0
	s_setprio 1
	v_mfma_f32_16x16x32_bf16 v[52:55], v[160:163], v[176:179], v[52:55]
	v_mfma_f32_16x16x32_bf16 v[48:51], v[168:171], v[176:179], v[48:51]
	v_mfma_f32_16x16x32_bf16 v[36:39], v[160:163], v[184:187], v[36:39]
	v_mfma_f32_16x16x32_bf16 v[32:35], v[168:171], v[184:187], v[32:35]
	v_mfma_f32_16x16x32_bf16 v[20:23], v[160:163], v[202:205], v[20:23]
	v_mfma_f32_16x16x32_bf16 v[16:19], v[168:171], v[202:205], v[16:19]
	v_mfma_f32_16x16x32_bf16 v[4:7], v[160:163], v[220:223], v[4:7]
	v_mfma_f32_16x16x32_bf16 v[0:3], v[168:171], v[220:223], v[0:3]
	v_mfma_f32_16x16x32_bf16 v[52:55], v[164:167], v[180:183], v[52:55]
	v_mfma_f32_16x16x32_bf16 v[48:51], v[172:175], v[180:183], v[48:51]
	v_mfma_f32_16x16x32_bf16 v[36:39], v[164:167], v[194:197], v[36:39]
	v_mfma_f32_16x16x32_bf16 v[32:35], v[172:175], v[194:197], v[32:35]
	v_mfma_f32_16x16x32_bf16 v[20:23], v[164:167], v[216:219], v[20:23]
	v_mfma_f32_16x16x32_bf16 v[16:19], v[172:175], v[216:219], v[16:19]
	v_mfma_f32_16x16x32_bf16 v[4:7], v[164:167], v[224:227], v[4:7]
	v_mfma_f32_16x16x32_bf16 v[0:3], v[172:175], v[224:227], v[0:3]
	s_setprio 0
	s_barrier
	s_add_u32 s38, s38, 0x100
	s_addc_u32 s39, s39, 0
	s_add_u32 s83, s83, 0x100
	s_addc_u32 s84, s84, 0
	s_cmp_ge_i32 s85, s60
	s_mov_b32 s48, s85
	s_cbranch_scc0 .LBB0_734
	s_mov_b64 s[88:89], 0x8000
